# S5 output GEMM epilogue: 32 per-step u loads + skip vector hoisted to the top of the epilogue, one wait (on top of s3+rev5+prioB)
# baseline (speedup 1.0000x reference)
.LBB0_2597:
	v_mov_b32_e32 v138, v0
	s_lshl_b32 s55, s0, 8
	v_and_or_b32 v146, v138, 15, s46
	v_lshrrev_b32_e32 v138, 2, v138
	v_and_b32_e32 v190, 12, v138
	s_lshl_b32 s14, s20, 4
	v_add_u32_e32 v140, s55, v146
	s_movk_i32 s0, 0x210
	s_mul_hi_i32 s17, s20, 0x300
	s_mul_i32 s16, s20, 0x300
	s_ashr_i32 s15, s14, 31
	v_cmp_gt_i32_e32 vcc, s0, v140
	v_lshlrev_b32_e32 v145, 2, v190
	v_lshlrev_b32_e32 v138, 1, v190
	v_readlane_b32 s22, v246, 9
	v_ashrrev_i32_e32 v141, 31, v140
	v_readlane_b32 s23, v246, 10
	v_lshl_add_u64 v[148:149], s[16:17], 0, v[140:141]
	v_readlane_b32 s0, v246, 49
	v_mov_b64_e32 v[142:143], s[22:23]
	s_movk_i32 s20, 0x600
	s_lshl_b32 s0, s0, 8
	v_mad_u64_u32 v[142:143], s[22:23], v148, s20, v[142:143]
	s_or_b32 s28, s0, s47
	v_mov_b32_e32 v148, v143
	v_or_b32_e32 v150, s28, v190
	v_mad_u64_u32 v[148:149], s[22:23], v149, s20, v[148:149]
	s_ashr_i32 s0, s28, 4
	v_mov_b32_e32 v143, v148
	v_ashrrev_i32_e32 v151, 31, v150
	s_lshl_b64 s[22:23], s[14:15], 2
	v_lshl_add_u64 v[148:149], v[150:151], 1, v[142:143]
	s_add_u32 s44, s48, s22
	s_addc_u32 s45, s49, s23
	v_mov_b32_e32 v156, v148
	v_mov_b32_e32 v157, v149
	s_mov_b32 s59, 0
	s_mov_b64 s[60:61], exec
	global_load_dwordx4 v[160:163], v145, s[44:45]
	s_mov_b64 exec, vcc
	global_load_dwordx2 v[164:165], v[156:157], off
	global_load_dwordx2 v[166:167], v[156:157], off offset:32
	global_load_dwordx2 v[168:169], v[156:157], off offset:256
	global_load_dwordx2 v[170:171], v[156:157], off offset:288
	s_mov_b64 exec, s[60:61]
	v_add_u32_e32 v147, 0x10, v140
	v_cmp_gt_i32_e32 vcc, 0x210, v147
	s_mov_b32 s58, 0x6000
	v_lshl_add_u64 v[158:159], v[156:157], 0, s[58:59]
	s_mov_b64 exec, vcc
	global_load_dwordx2 v[172:173], v[158:159], off
	global_load_dwordx2 v[174:175], v[158:159], off offset:32
	global_load_dwordx2 v[176:177], v[158:159], off offset:256
	global_load_dwordx2 v[178:179], v[158:159], off offset:288
	s_mov_b64 exec, s[60:61]
	v_add_u32_e32 v147, 0x20, v140
	v_cmp_gt_i32_e32 vcc, 0x210, v147
	s_mov_b32 s58, 0xc000
	v_lshl_add_u64 v[158:159], v[156:157], 0, s[58:59]
	s_mov_b64 exec, vcc
	global_load_dwordx2 v[180:181], v[158:159], off
	global_load_dwordx2 v[182:183], v[158:159], off offset:32
	global_load_dwordx2 v[184:185], v[158:159], off offset:256
	global_load_dwordx2 v[186:187], v[158:159], off offset:288
	s_mov_b64 exec, s[60:61]
	v_add_u32_e32 v147, 0x30, v140
	v_cmp_gt_i32_e32 vcc, 0x210, v147
	s_mov_b32 s58, 0x12000
	v_lshl_add_u64 v[158:159], v[156:157], 0, s[58:59]
	s_mov_b64 exec, vcc
	global_load_dwordx2 v[188:189], v[158:159], off
	global_load_dwordx2 v[192:193], v[158:159], off offset:32
	global_load_dwordx2 v[194:195], v[158:159], off offset:256
	global_load_dwordx2 v[196:197], v[158:159], off offset:288
	s_mov_b64 exec, s[60:61]
	v_add_u32_e32 v147, 0x80, v140
	v_cmp_gt_i32_e32 vcc, 0x210, v147
	s_mov_b32 s58, 0x30000
	v_lshl_add_u64 v[158:159], v[156:157], 0, s[58:59]
	s_mov_b64 exec, vcc
	global_load_dwordx2 v[198:199], v[158:159], off
	global_load_dwordx2 v[200:201], v[158:159], off offset:32
	global_load_dwordx2 v[202:203], v[158:159], off offset:256
	global_load_dwordx2 v[204:205], v[158:159], off offset:288
	s_mov_b64 exec, s[60:61]
	v_add_u32_e32 v147, 0x90, v140
	v_cmp_gt_i32_e32 vcc, 0x210, v147
	s_mov_b32 s58, 0x36000
	v_lshl_add_u64 v[158:159], v[156:157], 0, s[58:59]
	s_mov_b64 exec, vcc
	global_load_dwordx2 v[206:207], v[158:159], off
	global_load_dwordx2 v[208:209], v[158:159], off offset:32
	global_load_dwordx2 v[210:211], v[158:159], off offset:256
	global_load_dwordx2 v[212:213], v[158:159], off offset:288
	s_mov_b64 exec, s[60:61]
	v_add_u32_e32 v147, 0xa0, v140
	v_cmp_gt_i32_e32 vcc, 0x210, v147
	s_mov_b32 s58, 0x3c000
	v_lshl_add_u64 v[158:159], v[156:157], 0, s[58:59]
	s_mov_b64 exec, vcc
	global_load_dwordx2 v[214:215], v[158:159], off
	global_load_dwordx2 v[222:223], v[158:159], off offset:32
	global_load_dwordx2 v[224:225], v[158:159], off offset:256
	global_load_dwordx2 v[232:233], v[158:159], off offset:288
	s_mov_b64 exec, s[60:61]
	v_add_u32_e32 v147, 0xb0, v140
	v_cmp_gt_i32_e32 vcc, 0x210, v147
	s_mov_b32 s58, 0x42000
	v_lshl_add_u64 v[158:159], v[156:157], 0, s[58:59]
	s_mov_b64 exec, vcc
	global_load_dwordx2 v[234:235], v[158:159], off
	global_load_dwordx2 v[242:243], v[158:159], off offset:32
	global_load_dwordx2 v[244:245], v[158:159], off offset:256
	global_load_dwordx2 v[228:229], v[158:159], off offset:288
	s_mov_b64 exec, s[60:61]
	v_cmp_gt_i32_e32 vcc, 0x210, v140
	s_waitcnt vmcnt(0)
	s_and_saveexec_b64 s[18:19], vcc
	s_cbranch_execz .LBB0_2599
	v_readlane_b32 s22, v246, 9
	v_ashrrev_i32_e32 v141, 31, v140
	v_readlane_b32 s23, v246, 10
	v_lshl_add_u64 v[148:149], s[16:17], 0, v[140:141]
	v_readlane_b32 s0, v246, 49
	v_mov_b64_e32 v[142:143], s[22:23]
	s_movk_i32 s20, 0x600
	s_lshl_b32 s0, s0, 8
	v_mad_u64_u32 v[142:143], s[22:23], v148, s20, v[142:143]
	s_or_b32 s28, s0, s47
	v_mov_b32_e32 v148, v143
	v_or_b32_e32 v150, s28, v190
	v_mad_u64_u32 v[148:149], s[22:23], v149, s20, v[148:149]
	s_ashr_i32 s0, s28, 4
	v_mov_b32_e32 v143, v148
	v_ashrrev_i32_e32 v151, 31, v150
	s_lshl_b64 s[22:23], s[14:15], 2
	v_lshl_add_u64 v[148:149], v[150:151], 1, v[142:143]
	s_add_u32 s44, s48, s22
	s_nop 0
	s_addc_u32 s45, s49, s23
	s_nop 0
	v_lshlrev_b32_e32 v141, 5, v140
	v_readlane_b32 s56, v246, 17
	v_readlane_b32 s57, v246, 18
	s_lshl_b64 s[22:23], s[14:15], 1
	s_ashr_i32 s29, s28, 31
	s_nop 0
	v_lshlrev_b32_e32 v154, 16, v164
	v_and_b32_e32 v155, 0xffff0000, v164
	v_pk_fma_f32 v[126:127], v[160:161], v[154:155], v[126:127]
	s_nop 0
	v_mul_f32_e32 v139, 0x3d372713, v126
	v_mul_f32_e32 v139, v126, v139
	v_fma_f32 v139, v126, v139, v126
	v_mul_f32_e32 v139, 0x3f4c422a, v139
	v_add_f32_e32 v139, v139, v139
	v_mul_f32_e32 v139, 0x3fb8aa3b, v139
	v_exp_f32_e32 v139, v139
	s_nop 0
	v_add_f32_e32 v139, 1.0, v139
	v_rcp_f32_e32 v148, v139
	v_mul_f32_e32 v139, 0x3d372713, v127
	v_mul_f32_e32 v139, v127, v139
	v_fma_f32 v139, v127, v139, v127
	v_mul_f32_e32 v139, 0x3f4c422a, v139
	v_add_f32_e32 v139, v139, v139
	v_mul_f32_e32 v139, 0x3fb8aa3b, v139
	v_exp_f32_e32 v139, v139
	v_pk_mul_f32 v[126:127], v[126:127], 0.5 op_sel_hi:[1,0]
	v_add_f32_e32 v139, 1.0, v139
	v_rcp_f32_e32 v149, v139
	v_mov_b32_e32 v139, v191
	v_pk_fma_f32 v[148:149], v[148:149], 2.0, 1.0 op_sel_hi:[1,0,0] neg_lo:[1,0,0] neg_hi:[1,0,0]
	s_nop 0
	v_pk_add_f32 v[148:149], v[148:149], 1.0 op_sel_hi:[1,0]
	s_nop 0
	v_pk_mul_f32 v[126:127], v[126:127], v[148:149]
	v_lshlrev_b32_e32 v148, 16, v165
	v_and_b32_e32 v149, 0xffff0000, v165
	v_pk_fma_f32 v[128:129], v[162:163], v[148:149], v[128:129]
	v_cvt_pk_bf16_f32 v126, v126, v127
	v_mul_f32_e32 v127, 0x3d372713, v128
	v_mul_f32_e32 v127, v128, v127
	v_fma_f32 v127, v128, v127, v128
	v_mul_f32_e32 v127, 0x3f4c422a, v127
	v_add_f32_e32 v127, v127, v127
	v_mul_f32_e32 v127, 0x3fb8aa3b, v127
	v_exp_f32_e32 v127, v127
	s_nop 0
	v_add_f32_e32 v127, 1.0, v127
	v_rcp_f32_e32 v148, v127
	v_mul_f32_e32 v127, 0x3d372713, v129
	v_mul_f32_e32 v127, v129, v127
	v_fma_f32 v127, v129, v127, v129
	v_mul_f32_e32 v127, 0x3f4c422a, v127
	v_add_f32_e32 v127, v127, v127
	v_mul_f32_e32 v127, 0x3fb8aa3b, v127
	v_exp_f32_e32 v127, v127
	v_pk_mul_f32 v[128:129], v[128:129], 0.5 op_sel_hi:[1,0]
	v_add_f32_e32 v127, 1.0, v127
	v_rcp_f32_e32 v149, v127
	s_nop 0
	v_pk_fma_f32 v[148:149], v[148:149], 2.0, 1.0 op_sel_hi:[1,0,0] neg_lo:[1,0,0] neg_hi:[1,0,0]
	s_nop 0
	v_pk_add_f32 v[148:149], v[148:149], 1.0 op_sel_hi:[1,0]
	s_nop 0
	v_pk_mul_f32 v[128:129], v[128:129], v[148:149]
	s_nop 0
	v_cvt_pk_bf16_f32 v127, v128, v129
	v_add_u32_e32 v128, s0, v141
	v_ashrrev_i32_e32 v129, 31, v128
	v_lshlrev_b64 v[128:129], 10, v[128:129]
	v_lshl_add_u64 v[128:129], s[56:57], 0, v[128:129]
	v_lshl_add_u64 v[128:129], v[128:129], 0, s[22:23]
	v_lshl_add_u64 v[128:129], v[128:129], 0, v[138:139]
	global_store_dwordx2 v[128:129], v[126:127], off
	v_lshl_add_u64 v[126:127], s[28:29], 0, v[190:191]
	v_lshl_add_u64 v[126:127], v[126:127], 1, v[142:143]
	s_nop 0
	s_nop 0
	s_or_b32 s0, s28, 16
	s_ashr_i32 s0, s0, 4
	s_nop 0
	v_lshlrev_b32_e32 v142, 16, v166
	v_and_b32_e32 v143, 0xffff0000, v166
	s_nop 0
	v_pk_fma_f32 v[122:123], v[160:161], v[142:143], v[122:123]
	s_nop 0
	v_mul_f32_e32 v128, 0x3d372713, v122
	v_mul_f32_e32 v128, v122, v128
	v_fma_f32 v128, v122, v128, v122
	v_mul_f32_e32 v128, 0x3f4c422a, v128
	v_add_f32_e32 v128, v128, v128
	v_mul_f32_e32 v128, 0x3fb8aa3b, v128
	v_exp_f32_e32 v128, v128
	s_nop 0
	v_add_f32_e32 v128, 1.0, v128
	v_rcp_f32_e32 v142, v128
	v_mul_f32_e32 v128, 0x3d372713, v123
	v_mul_f32_e32 v128, v123, v128
	v_fma_f32 v128, v123, v128, v123
	v_mul_f32_e32 v128, 0x3f4c422a, v128
	v_add_f32_e32 v128, v128, v128
	v_mul_f32_e32 v128, 0x3fb8aa3b, v128
	v_exp_f32_e32 v128, v128
	v_pk_mul_f32 v[122:123], v[122:123], 0.5 op_sel_hi:[1,0]
	v_add_f32_e32 v128, 1.0, v128
	v_rcp_f32_e32 v143, v128
	v_lshlrev_b32_e32 v128, 16, v167
	v_and_b32_e32 v129, 0xffff0000, v167
	v_pk_fma_f32 v[124:125], v[162:163], v[128:129], v[124:125]
	v_pk_fma_f32 v[142:143], v[142:143], 2.0, 1.0 op_sel_hi:[1,0,0] neg_lo:[1,0,0] neg_hi:[1,0,0]
	s_nop 0
	v_pk_add_f32 v[142:143], v[142:143], 1.0 op_sel_hi:[1,0]
	s_nop 0
	v_pk_mul_f32 v[122:123], v[122:123], v[142:143]
	s_nop 0
	v_cvt_pk_bf16_f32 v122, v122, v123
	v_mul_f32_e32 v123, 0x3d372713, v124
	v_mul_f32_e32 v123, v124, v123
	v_fma_f32 v123, v124, v123, v124
	v_mul_f32_e32 v123, 0x3f4c422a, v123
	v_add_f32_e32 v123, v123, v123
	v_mul_f32_e32 v123, 0x3fb8aa3b, v123
	v_exp_f32_e32 v123, v123
	s_nop 0
	v_add_f32_e32 v123, 1.0, v123
	v_rcp_f32_e32 v128, v123
	v_mul_f32_e32 v123, 0x3d372713, v125
	v_mul_f32_e32 v123, v125, v123
	v_fma_f32 v123, v125, v123, v125
	v_mul_f32_e32 v123, 0x3f4c422a, v123
	v_add_f32_e32 v123, v123, v123
	v_mul_f32_e32 v123, 0x3fb8aa3b, v123
	v_exp_f32_e32 v123, v123
	v_pk_mul_f32 v[124:125], v[124:125], 0.5 op_sel_hi:[1,0]
	v_add_f32_e32 v123, 1.0, v123
	v_rcp_f32_e32 v129, v123
	s_nop 0
	v_pk_fma_f32 v[128:129], v[128:129], 2.0, 1.0 op_sel_hi:[1,0,0] neg_lo:[1,0,0] neg_hi:[1,0,0]
	s_nop 0
	v_pk_add_f32 v[128:129], v[128:129], 1.0 op_sel_hi:[1,0]
	s_nop 0
	v_pk_mul_f32 v[124:125], v[124:125], v[128:129]
	s_nop 0
	v_cvt_pk_bf16_f32 v123, v124, v125
	v_add_u32_e32 v124, s0, v141
	v_ashrrev_i32_e32 v125, 31, v124
	v_lshlrev_b64 v[124:125], 10, v[124:125]
	v_lshl_add_u64 v[124:125], s[56:57], 0, v[124:125]
	v_lshl_add_u64 v[124:125], v[124:125], 0, s[22:23]
	v_lshl_add_u64 v[124:125], v[124:125], 0, v[138:139]
	global_store_dwordx2 v[124:125], v[122:123], off
	s_nop 0
	s_nop 0
	s_nop 0
	s_or_b32 s0, s28, 0x80
	s_ashr_i32 s0, s0, 4
	s_nop 0
	v_lshlrev_b32_e32 v142, 16, v168
	v_and_b32_e32 v143, 0xffff0000, v168
	s_nop 0
	v_pk_fma_f32 v[118:119], v[160:161], v[142:143], v[118:119]
	s_nop 0
	v_mul_f32_e32 v122, 0x3d372713, v118
	v_mul_f32_e32 v123, 0x3d372713, v119
	v_mul_f32_e32 v122, v118, v122
	v_mul_f32_e32 v123, v119, v123
	v_fma_f32 v122, v118, v122, v118
	v_fma_f32 v123, v119, v123, v119
	v_mul_f32_e32 v122, 0x3f4c422a, v122
	v_mul_f32_e32 v123, 0x3f4c422a, v123
	v_add_f32_e32 v122, v122, v122
	v_add_f32_e32 v123, v123, v123
	v_mul_f32_e32 v122, 0x3fb8aa3b, v122
	v_mul_f32_e32 v123, 0x3fb8aa3b, v123
	v_exp_f32_e32 v122, v122
	v_exp_f32_e32 v123, v123
	v_pk_mul_f32 v[118:119], v[118:119], 0.5 op_sel_hi:[1,0]
	v_add_f32_e32 v122, 1.0, v122
	v_add_f32_e32 v123, 1.0, v123
	v_rcp_f32_e32 v122, v122
	v_rcp_f32_e32 v123, v123
	s_nop 0
	v_pk_fma_f32 v[122:123], v[122:123], 2.0, 1.0 op_sel_hi:[1,0,0] neg_lo:[1,0,0] neg_hi:[1,0,0]
	s_nop 0
	v_pk_add_f32 v[122:123], v[122:123], 1.0 op_sel_hi:[1,0]
	s_nop 0
	v_pk_mul_f32 v[118:119], v[118:119], v[122:123]
	v_lshlrev_b32_e32 v122, 16, v169
	v_and_b32_e32 v123, 0xffff0000, v169
	v_pk_fma_f32 v[120:121], v[162:163], v[122:123], v[120:121]
	v_cvt_pk_bf16_f32 v118, v118, v119
	v_mul_f32_e32 v119, 0x3d372713, v120
	v_mul_f32_e32 v119, v120, v119
	v_fma_f32 v119, v120, v119, v120
	v_mul_f32_e32 v119, 0x3f4c422a, v119
	v_add_f32_e32 v119, v119, v119
	v_mul_f32_e32 v119, 0x3fb8aa3b, v119
	v_exp_f32_e32 v119, v119
	s_nop 0
	v_add_f32_e32 v119, 1.0, v119
	v_rcp_f32_e32 v122, v119
	v_mul_f32_e32 v119, 0x3d372713, v121
	v_mul_f32_e32 v119, v121, v119
	v_fma_f32 v119, v121, v119, v121
	v_mul_f32_e32 v119, 0x3f4c422a, v119
	v_add_f32_e32 v119, v119, v119
	v_mul_f32_e32 v119, 0x3fb8aa3b, v119
	v_exp_f32_e32 v119, v119
	v_pk_mul_f32 v[120:121], v[120:121], 0.5 op_sel_hi:[1,0]
	v_add_f32_e32 v119, 1.0, v119
	v_rcp_f32_e32 v123, v119
	s_nop 0
	v_pk_fma_f32 v[122:123], v[122:123], 2.0, 1.0 op_sel_hi:[1,0,0] neg_lo:[1,0,0] neg_hi:[1,0,0]
	s_nop 0
	v_pk_add_f32 v[122:123], v[122:123], 1.0 op_sel_hi:[1,0]
	s_nop 0
	v_pk_mul_f32 v[120:121], v[120:121], v[122:123]
	s_nop 0
	v_cvt_pk_bf16_f32 v119, v120, v121
	v_add_u32_e32 v120, s0, v141
	v_ashrrev_i32_e32 v121, 31, v120
	v_lshlrev_b64 v[120:121], 10, v[120:121]
	v_lshl_add_u64 v[120:121], s[56:57], 0, v[120:121]
	v_lshl_add_u64 v[120:121], v[120:121], 0, s[22:23]
	v_lshl_add_u64 v[120:121], v[120:121], 0, v[138:139]
	global_store_dwordx2 v[120:121], v[118:119], off
	s_nop 0
	s_nop 0
	s_nop 0
	s_or_b32 s0, s28, 0x90
	s_ashr_i32 s0, s0, 4
	s_nop 0
	v_lshlrev_b32_e32 v124, 16, v170
	v_and_b32_e32 v125, 0xffff0000, v170
	s_nop 0
	v_pk_fma_f32 v[114:115], v[160:161], v[124:125], v[114:115]
	s_nop 0
	v_mul_f32_e32 v118, 0x3d372713, v114
	v_mul_f32_e32 v119, 0x3d372713, v115
	v_mul_f32_e32 v118, v114, v118
	v_mul_f32_e32 v119, v115, v119
	v_fma_f32 v118, v114, v118, v114
	v_fma_f32 v119, v115, v119, v115
	v_mul_f32_e32 v118, 0x3f4c422a, v118
	v_mul_f32_e32 v119, 0x3f4c422a, v119
	v_add_f32_e32 v118, v118, v118
	v_add_f32_e32 v119, v119, v119
	v_mul_f32_e32 v118, 0x3fb8aa3b, v118
	v_mul_f32_e32 v119, 0x3fb8aa3b, v119
	v_exp_f32_e32 v118, v118
	v_exp_f32_e32 v119, v119
	v_pk_mul_f32 v[114:115], v[114:115], 0.5 op_sel_hi:[1,0]
	v_add_f32_e32 v118, 1.0, v118
	v_add_f32_e32 v119, 1.0, v119
	v_rcp_f32_e32 v118, v118
	v_rcp_f32_e32 v119, v119
	s_nop 0
	v_pk_fma_f32 v[118:119], v[118:119], 2.0, 1.0 op_sel_hi:[1,0,0] neg_lo:[1,0,0] neg_hi:[1,0,0]
	s_nop 0
	v_pk_add_f32 v[118:119], v[118:119], 1.0 op_sel_hi:[1,0]
	s_nop 0
	v_pk_mul_f32 v[114:115], v[114:115], v[118:119]
	v_lshlrev_b32_e32 v118, 16, v171
	v_and_b32_e32 v119, 0xffff0000, v171
	v_pk_fma_f32 v[116:117], v[162:163], v[118:119], v[116:117]
	v_cvt_pk_bf16_f32 v114, v114, v115
	v_mul_f32_e32 v115, 0x3d372713, v116
	v_mul_f32_e32 v115, v116, v115
	v_fma_f32 v115, v116, v115, v116
	v_mul_f32_e32 v115, 0x3f4c422a, v115
	v_add_f32_e32 v115, v115, v115
	v_mul_f32_e32 v115, 0x3fb8aa3b, v115
	v_exp_f32_e32 v115, v115
	s_nop 0
	v_add_f32_e32 v115, 1.0, v115
	v_rcp_f32_e32 v118, v115
	v_mul_f32_e32 v115, 0x3d372713, v117
	v_mul_f32_e32 v115, v117, v115
	v_fma_f32 v115, v117, v115, v117
	v_mul_f32_e32 v115, 0x3f4c422a, v115
	v_add_f32_e32 v115, v115, v115
	v_mul_f32_e32 v115, 0x3fb8aa3b, v115
	v_exp_f32_e32 v115, v115
	v_pk_mul_f32 v[116:117], v[116:117], 0.5 op_sel_hi:[1,0]
	v_add_f32_e32 v115, 1.0, v115
	v_rcp_f32_e32 v119, v115
	s_nop 0
	v_pk_fma_f32 v[118:119], v[118:119], 2.0, 1.0 op_sel_hi:[1,0,0] neg_lo:[1,0,0] neg_hi:[1,0,0]
	s_nop 0
	v_pk_add_f32 v[118:119], v[118:119], 1.0 op_sel_hi:[1,0]
	s_nop 0
	v_pk_mul_f32 v[116:117], v[116:117], v[118:119]
	s_nop 0
	v_cvt_pk_bf16_f32 v115, v116, v117
	v_add_u32_e32 v116, s0, v141
	v_ashrrev_i32_e32 v117, 31, v116
	v_lshlrev_b64 v[116:117], 10, v[116:117]
	v_lshl_add_u64 v[116:117], s[56:57], 0, v[116:117]
	v_lshl_add_u64 v[116:117], v[116:117], 0, s[22:23]
	v_lshl_add_u64 v[116:117], v[116:117], 0, v[138:139]
	global_store_dwordx2 v[116:117], v[114:115], off
.LBB0_2599:
	s_or_b64 exec, exec, s[18:19]
	v_add3_u32 v114, s55, v146, 16
	s_movk_i32 s0, 0x210
	v_cmp_gt_i32_e32 vcc, s0, v114
	s_and_saveexec_b64 s[18:19], vcc
	s_cbranch_execz .LBB0_2601
	v_readlane_b32 s22, v246, 9
	v_ashrrev_i32_e32 v115, 31, v114
	v_readlane_b32 s23, v246, 10
	v_lshl_add_u64 v[118:119], s[16:17], 0, v[114:115]
	v_lshlrev_b32_e32 v116, 5, v114
	v_readlane_b32 s0, v246, 49
	v_mov_b64_e32 v[114:115], s[22:23]
	s_movk_i32 s20, 0x600
	s_lshl_b32 s0, s0, 8
	v_mad_u64_u32 v[114:115], s[22:23], v118, s20, v[114:115]
	s_or_b32 s28, s0, s47
	v_mov_b32_e32 v118, v115
	v_or_b32_e32 v120, s28, v190
	v_mad_u64_u32 v[118:119], s[22:23], v119, s20, v[118:119]
	s_ashr_i32 s0, s28, 4
	v_mov_b32_e32 v115, v118
	v_ashrrev_i32_e32 v121, 31, v120
	s_lshl_b64 s[22:23], s[14:15], 2
	v_lshl_add_u64 v[118:119], v[120:121], 1, v[114:115]
	s_add_u32 s44, s48, s22
	s_nop 0
	s_addc_u32 s45, s49, s23
	s_nop 0
	v_readlane_b32 s56, v246, 17
	v_readlane_b32 s57, v246, 18
	s_lshl_b64 s[22:23], s[14:15], 1
	v_mov_b32_e32 v139, v191
	s_ashr_i32 s29, s28, 31
	s_nop 0
	v_lshlrev_b32_e32 v124, 16, v172
	v_and_b32_e32 v125, 0xffff0000, v172
	v_pk_fma_f32 v[110:111], v[160:161], v[124:125], v[110:111]
	s_nop 0
	v_mul_f32_e32 v117, 0x3d372713, v110
	v_mul_f32_e32 v117, v110, v117
	v_fma_f32 v117, v110, v117, v110
	v_mul_f32_e32 v117, 0x3f4c422a, v117
	v_add_f32_e32 v117, v117, v117
	v_mul_f32_e32 v117, 0x3fb8aa3b, v117
	v_exp_f32_e32 v117, v117
	s_nop 0
	v_add_f32_e32 v117, 1.0, v117
	v_rcp_f32_e32 v118, v117
	v_mul_f32_e32 v117, 0x3d372713, v111
	v_mul_f32_e32 v117, v111, v117
	v_fma_f32 v117, v111, v117, v111
	v_mul_f32_e32 v117, 0x3f4c422a, v117
	v_add_f32_e32 v117, v117, v117
	v_mul_f32_e32 v117, 0x3fb8aa3b, v117
	v_exp_f32_e32 v117, v117
	v_pk_mul_f32 v[110:111], v[110:111], 0.5 op_sel_hi:[1,0]
	v_add_f32_e32 v117, 1.0, v117
	v_rcp_f32_e32 v119, v117
	s_nop 0
	v_pk_fma_f32 v[118:119], v[118:119], 2.0, 1.0 op_sel_hi:[1,0,0] neg_lo:[1,0,0] neg_hi:[1,0,0]
	s_nop 0
	v_pk_add_f32 v[118:119], v[118:119], 1.0 op_sel_hi:[1,0]
	s_nop 0
	v_pk_mul_f32 v[110:111], v[110:111], v[118:119]
	v_lshlrev_b32_e32 v118, 16, v173
	v_and_b32_e32 v119, 0xffff0000, v173
	v_pk_fma_f32 v[112:113], v[162:163], v[118:119], v[112:113]
	v_cvt_pk_bf16_f32 v110, v110, v111
	v_mul_f32_e32 v111, 0x3d372713, v112
	v_mul_f32_e32 v111, v112, v111
	v_fma_f32 v111, v112, v111, v112
	v_mul_f32_e32 v111, 0x3f4c422a, v111
	v_add_f32_e32 v111, v111, v111
	v_mul_f32_e32 v111, 0x3fb8aa3b, v111
	v_exp_f32_e32 v111, v111
	s_nop 0
	v_add_f32_e32 v111, 1.0, v111
	v_rcp_f32_e32 v118, v111
	v_mul_f32_e32 v111, 0x3d372713, v113
	v_mul_f32_e32 v111, v113, v111
	v_fma_f32 v111, v113, v111, v113
	v_mul_f32_e32 v111, 0x3f4c422a, v111
	v_add_f32_e32 v111, v111, v111
	v_mul_f32_e32 v111, 0x3fb8aa3b, v111
	v_exp_f32_e32 v111, v111
	v_pk_mul_f32 v[112:113], v[112:113], 0.5 op_sel_hi:[1,0]
	v_add_f32_e32 v111, 1.0, v111
	v_rcp_f32_e32 v119, v111
	s_nop 0
	v_pk_fma_f32 v[118:119], v[118:119], 2.0, 1.0 op_sel_hi:[1,0,0] neg_lo:[1,0,0] neg_hi:[1,0,0]
	s_nop 0
	v_pk_add_f32 v[118:119], v[118:119], 1.0 op_sel_hi:[1,0]
	s_nop 0
	v_pk_mul_f32 v[112:113], v[112:113], v[118:119]
	s_nop 0
	v_cvt_pk_bf16_f32 v111, v112, v113
	v_add_u32_e32 v112, s0, v116
	v_ashrrev_i32_e32 v113, 31, v112
	v_lshlrev_b64 v[112:113], 10, v[112:113]
	v_lshl_add_u64 v[112:113], s[56:57], 0, v[112:113]
	v_lshl_add_u64 v[112:113], v[112:113], 0, s[22:23]
	v_lshl_add_u64 v[112:113], v[112:113], 0, v[138:139]
	global_store_dwordx2 v[112:113], v[110:111], off
	v_lshl_add_u64 v[110:111], s[28:29], 0, v[190:191]
	v_lshl_add_u64 v[110:111], v[110:111], 1, v[114:115]
	s_nop 0
	s_nop 0
	s_or_b32 s0, s28, 16
	s_ashr_i32 s0, s0, 4
	s_nop 0
	v_lshlrev_b32_e32 v120, 16, v174
	v_and_b32_e32 v121, 0xffff0000, v174
	s_nop 0
	v_pk_fma_f32 v[106:107], v[160:161], v[120:121], v[106:107]
	s_nop 0
	v_mul_f32_e32 v112, 0x3d372713, v106
	v_mul_f32_e32 v113, 0x3d372713, v107
	v_mul_f32_e32 v112, v106, v112
	v_mul_f32_e32 v113, v107, v113
	v_fma_f32 v112, v106, v112, v106
	v_fma_f32 v113, v107, v113, v107
	v_mul_f32_e32 v112, 0x3f4c422a, v112
	v_mul_f32_e32 v113, 0x3f4c422a, v113
	v_add_f32_e32 v112, v112, v112
	v_add_f32_e32 v113, v113, v113
	v_mul_f32_e32 v112, 0x3fb8aa3b, v112
	v_mul_f32_e32 v113, 0x3fb8aa3b, v113
	v_exp_f32_e32 v112, v112
	v_exp_f32_e32 v113, v113
	v_pk_mul_f32 v[106:107], v[106:107], 0.5 op_sel_hi:[1,0]
	v_add_f32_e32 v112, 1.0, v112
	v_add_f32_e32 v113, 1.0, v113
	v_rcp_f32_e32 v112, v112
	v_rcp_f32_e32 v113, v113
	s_nop 0
	v_pk_fma_f32 v[112:113], v[112:113], 2.0, 1.0 op_sel_hi:[1,0,0] neg_lo:[1,0,0] neg_hi:[1,0,0]
	s_nop 0
	v_pk_add_f32 v[112:113], v[112:113], 1.0 op_sel_hi:[1,0]
	s_nop 0
	v_pk_mul_f32 v[106:107], v[106:107], v[112:113]
	v_lshlrev_b32_e32 v112, 16, v175
	v_and_b32_e32 v113, 0xffff0000, v175
	v_pk_fma_f32 v[108:109], v[162:163], v[112:113], v[108:109]
	v_cvt_pk_bf16_f32 v106, v106, v107
	v_mul_f32_e32 v107, 0x3d372713, v108
	v_mul_f32_e32 v107, v108, v107
	v_fma_f32 v107, v108, v107, v108
	v_mul_f32_e32 v107, 0x3f4c422a, v107
	v_add_f32_e32 v107, v107, v107
	v_mul_f32_e32 v107, 0x3fb8aa3b, v107
	v_exp_f32_e32 v107, v107
	s_nop 0
	v_add_f32_e32 v107, 1.0, v107
	v_rcp_f32_e32 v112, v107
	v_mul_f32_e32 v107, 0x3d372713, v109
	v_mul_f32_e32 v107, v109, v107
	v_fma_f32 v107, v109, v107, v109
	v_mul_f32_e32 v107, 0x3f4c422a, v107
	v_add_f32_e32 v107, v107, v107
	v_mul_f32_e32 v107, 0x3fb8aa3b, v107
	v_exp_f32_e32 v107, v107
	v_pk_mul_f32 v[108:109], v[108:109], 0.5 op_sel_hi:[1,0]
	v_add_f32_e32 v107, 1.0, v107
	v_rcp_f32_e32 v113, v107
	s_nop 0
	v_pk_fma_f32 v[112:113], v[112:113], 2.0, 1.0 op_sel_hi:[1,0,0] neg_lo:[1,0,0] neg_hi:[1,0,0]
	s_nop 0
	v_pk_add_f32 v[112:113], v[112:113], 1.0 op_sel_hi:[1,0]
	s_nop 0
	v_pk_mul_f32 v[108:109], v[108:109], v[112:113]
	s_nop 0
	v_cvt_pk_bf16_f32 v107, v108, v109
	v_add_u32_e32 v108, s0, v116
	v_ashrrev_i32_e32 v109, 31, v108
	v_lshlrev_b64 v[108:109], 10, v[108:109]
	v_lshl_add_u64 v[108:109], s[56:57], 0, v[108:109]
	v_lshl_add_u64 v[108:109], v[108:109], 0, s[22:23]
	v_lshl_add_u64 v[108:109], v[108:109], 0, v[138:139]
	global_store_dwordx2 v[108:109], v[106:107], off
	s_nop 0
	s_nop 0
	s_nop 0
	s_or_b32 s0, s28, 0x80
	s_ashr_i32 s0, s0, 4
	s_nop 0
	v_lshlrev_b32_e32 v114, 16, v176
	v_and_b32_e32 v115, 0xffff0000, v176
	s_nop 0
	v_pk_fma_f32 v[102:103], v[160:161], v[114:115], v[102:103]
	s_nop 0
	v_mul_f32_e32 v106, 0x3d372713, v102
	v_mul_f32_e32 v107, 0x3d372713, v103
	v_mul_f32_e32 v106, v102, v106
	v_mul_f32_e32 v107, v103, v107
	v_fma_f32 v106, v102, v106, v102
	v_fma_f32 v107, v103, v107, v103
	v_mul_f32_e32 v106, 0x3f4c422a, v106
	v_mul_f32_e32 v107, 0x3f4c422a, v107
	v_add_f32_e32 v106, v106, v106
	v_add_f32_e32 v107, v107, v107
	v_mul_f32_e32 v106, 0x3fb8aa3b, v106
	v_mul_f32_e32 v107, 0x3fb8aa3b, v107
	v_exp_f32_e32 v106, v106
	v_exp_f32_e32 v107, v107
	v_pk_mul_f32 v[102:103], v[102:103], 0.5 op_sel_hi:[1,0]
	v_add_f32_e32 v106, 1.0, v106
	v_add_f32_e32 v107, 1.0, v107
	v_rcp_f32_e32 v106, v106
	v_rcp_f32_e32 v107, v107
	s_nop 0
	v_pk_fma_f32 v[106:107], v[106:107], 2.0, 1.0 op_sel_hi:[1,0,0] neg_lo:[1,0,0] neg_hi:[1,0,0]
	s_nop 0
	v_pk_add_f32 v[106:107], v[106:107], 1.0 op_sel_hi:[1,0]
	s_nop 0
	v_pk_mul_f32 v[102:103], v[102:103], v[106:107]
	v_lshlrev_b32_e32 v106, 16, v177
	v_and_b32_e32 v107, 0xffff0000, v177
	v_pk_fma_f32 v[104:105], v[162:163], v[106:107], v[104:105]
	v_cvt_pk_bf16_f32 v102, v102, v103
	v_mul_f32_e32 v103, 0x3d372713, v104
	v_mul_f32_e32 v103, v104, v103
	v_fma_f32 v103, v104, v103, v104
	v_mul_f32_e32 v103, 0x3f4c422a, v103
	v_add_f32_e32 v103, v103, v103
	v_mul_f32_e32 v103, 0x3fb8aa3b, v103
	v_exp_f32_e32 v103, v103
	s_nop 0
	v_add_f32_e32 v103, 1.0, v103
	v_rcp_f32_e32 v106, v103
	v_mul_f32_e32 v103, 0x3d372713, v105
	v_mul_f32_e32 v103, v105, v103
	v_fma_f32 v103, v105, v103, v105
	v_mul_f32_e32 v103, 0x3f4c422a, v103
	v_add_f32_e32 v103, v103, v103
	v_mul_f32_e32 v103, 0x3fb8aa3b, v103
	v_exp_f32_e32 v103, v103
	v_pk_mul_f32 v[104:105], v[104:105], 0.5 op_sel_hi:[1,0]
	v_add_f32_e32 v103, 1.0, v103
	v_rcp_f32_e32 v107, v103
	s_nop 0
	v_pk_fma_f32 v[106:107], v[106:107], 2.0, 1.0 op_sel_hi:[1,0,0] neg_lo:[1,0,0] neg_hi:[1,0,0]
	s_nop 0
	v_pk_add_f32 v[106:107], v[106:107], 1.0 op_sel_hi:[1,0]
	s_nop 0
	v_pk_mul_f32 v[104:105], v[104:105], v[106:107]
	s_nop 0
	v_cvt_pk_bf16_f32 v103, v104, v105
	v_add_u32_e32 v104, s0, v116
	v_ashrrev_i32_e32 v105, 31, v104
	v_lshlrev_b64 v[104:105], 10, v[104:105]
	v_lshl_add_u64 v[104:105], s[56:57], 0, v[104:105]
	v_lshl_add_u64 v[104:105], v[104:105], 0, s[22:23]
	v_lshl_add_u64 v[104:105], v[104:105], 0, v[138:139]
	global_store_dwordx2 v[104:105], v[102:103], off
	s_nop 0
	s_nop 0
	s_nop 0
	s_or_b32 s0, s28, 0x90
	s_ashr_i32 s0, s0, 4
	s_nop 0
	v_lshlrev_b32_e32 v108, 16, v178
	v_and_b32_e32 v109, 0xffff0000, v178
	s_nop 0
	v_pk_fma_f32 v[98:99], v[160:161], v[108:109], v[98:99]
	s_nop 0
	v_mul_f32_e32 v102, 0x3d372713, v98
	v_mul_f32_e32 v103, 0x3d372713, v99
	v_mul_f32_e32 v102, v98, v102
	v_mul_f32_e32 v103, v99, v103
	v_fma_f32 v102, v98, v102, v98
	v_fma_f32 v103, v99, v103, v99
	v_mul_f32_e32 v102, 0x3f4c422a, v102
	v_mul_f32_e32 v103, 0x3f4c422a, v103
	v_add_f32_e32 v102, v102, v102
	v_add_f32_e32 v103, v103, v103
	v_mul_f32_e32 v102, 0x3fb8aa3b, v102
	v_mul_f32_e32 v103, 0x3fb8aa3b, v103
	v_exp_f32_e32 v102, v102
	v_exp_f32_e32 v103, v103
	v_pk_mul_f32 v[98:99], v[98:99], 0.5 op_sel_hi:[1,0]
	v_add_f32_e32 v102, 1.0, v102
	v_add_f32_e32 v103, 1.0, v103
	v_rcp_f32_e32 v102, v102
	v_rcp_f32_e32 v103, v103
	s_nop 0
	v_pk_fma_f32 v[102:103], v[102:103], 2.0, 1.0 op_sel_hi:[1,0,0] neg_lo:[1,0,0] neg_hi:[1,0,0]
	s_nop 0
	v_pk_add_f32 v[102:103], v[102:103], 1.0 op_sel_hi:[1,0]
	s_nop 0
	v_pk_mul_f32 v[98:99], v[98:99], v[102:103]
	v_lshlrev_b32_e32 v102, 16, v179
	v_and_b32_e32 v103, 0xffff0000, v179
	v_pk_fma_f32 v[100:101], v[162:163], v[102:103], v[100:101]
	v_cvt_pk_bf16_f32 v98, v98, v99
	v_mul_f32_e32 v99, 0x3d372713, v100
	v_mul_f32_e32 v99, v100, v99
	v_fma_f32 v99, v100, v99, v100
	v_mul_f32_e32 v99, 0x3f4c422a, v99
	v_add_f32_e32 v99, v99, v99
	v_mul_f32_e32 v99, 0x3fb8aa3b, v99
	v_exp_f32_e32 v99, v99
	s_nop 0
	v_add_f32_e32 v99, 1.0, v99
	v_rcp_f32_e32 v102, v99
	v_mul_f32_e32 v99, 0x3d372713, v101
	v_mul_f32_e32 v99, v101, v99
	v_fma_f32 v99, v101, v99, v101
	v_mul_f32_e32 v99, 0x3f4c422a, v99
	v_add_f32_e32 v99, v99, v99
	v_mul_f32_e32 v99, 0x3fb8aa3b, v99
	v_exp_f32_e32 v99, v99
	v_pk_mul_f32 v[100:101], v[100:101], 0.5 op_sel_hi:[1,0]
	v_add_f32_e32 v99, 1.0, v99
	v_rcp_f32_e32 v103, v99
	s_nop 0
	v_pk_fma_f32 v[102:103], v[102:103], 2.0, 1.0 op_sel_hi:[1,0,0] neg_lo:[1,0,0] neg_hi:[1,0,0]
	s_nop 0
	v_pk_add_f32 v[102:103], v[102:103], 1.0 op_sel_hi:[1,0]
	s_nop 0
	v_pk_mul_f32 v[100:101], v[100:101], v[102:103]
	s_nop 0
	v_cvt_pk_bf16_f32 v99, v100, v101
	v_add_u32_e32 v100, s0, v116
	v_ashrrev_i32_e32 v101, 31, v100
	v_lshlrev_b64 v[100:101], 10, v[100:101]
	v_lshl_add_u64 v[100:101], s[56:57], 0, v[100:101]
	v_lshl_add_u64 v[100:101], v[100:101], 0, s[22:23]
	v_lshl_add_u64 v[100:101], v[100:101], 0, v[138:139]
	global_store_dwordx2 v[100:101], v[98:99], off
.LBB0_2601:
	s_or_b64 exec, exec, s[18:19]
	v_add3_u32 v98, s55, v146, 32
	s_movk_i32 s0, 0x210
	v_cmp_gt_i32_e32 vcc, s0, v98
	s_and_saveexec_b64 s[18:19], vcc
	s_cbranch_execz .LBB0_2603
	v_readlane_b32 s22, v246, 9
	v_ashrrev_i32_e32 v99, 31, v98
	v_readlane_b32 s23, v246, 10
	v_lshl_add_u64 v[102:103], s[16:17], 0, v[98:99]
	v_lshlrev_b32_e32 v100, 5, v98
	v_readlane_b32 s0, v246, 49
	v_mov_b64_e32 v[98:99], s[22:23]
	s_movk_i32 s20, 0x600
	s_lshl_b32 s0, s0, 8
	v_mad_u64_u32 v[98:99], s[22:23], v102, s20, v[98:99]
	s_or_b32 s28, s0, s47
	v_mov_b32_e32 v102, v99
	v_or_b32_e32 v104, s28, v190
	v_mad_u64_u32 v[102:103], s[22:23], v103, s20, v[102:103]
	s_ashr_i32 s0, s28, 4
	v_mov_b32_e32 v99, v102
	v_ashrrev_i32_e32 v105, 31, v104
	s_lshl_b64 s[22:23], s[14:15], 2
	v_lshl_add_u64 v[102:103], v[104:105], 1, v[98:99]
	s_add_u32 s44, s48, s22
	s_nop 0
	s_addc_u32 s45, s49, s23
	s_nop 0
	v_readlane_b32 s56, v246, 17
	v_readlane_b32 s57, v246, 18
	s_lshl_b64 s[22:23], s[14:15], 1
	v_mov_b32_e32 v139, v191
	s_ashr_i32 s29, s28, 31
	s_nop 0
	v_lshlrev_b32_e32 v108, 16, v180
	v_and_b32_e32 v109, 0xffff0000, v180
	v_pk_fma_f32 v[94:95], v[160:161], v[108:109], v[94:95]
	s_nop 0
	v_mul_f32_e32 v101, 0x3d372713, v94
	v_mul_f32_e32 v101, v94, v101
	v_fma_f32 v101, v94, v101, v94
	v_mul_f32_e32 v101, 0x3f4c422a, v101
	v_add_f32_e32 v101, v101, v101
	v_mul_f32_e32 v101, 0x3fb8aa3b, v101
	v_exp_f32_e32 v101, v101
	s_nop 0
	v_add_f32_e32 v101, 1.0, v101
	v_rcp_f32_e32 v102, v101
	v_mul_f32_e32 v101, 0x3d372713, v95
	v_mul_f32_e32 v101, v95, v101
	v_fma_f32 v101, v95, v101, v95
	v_mul_f32_e32 v101, 0x3f4c422a, v101
	v_add_f32_e32 v101, v101, v101
	v_mul_f32_e32 v101, 0x3fb8aa3b, v101
	v_exp_f32_e32 v101, v101
	v_pk_mul_f32 v[94:95], v[94:95], 0.5 op_sel_hi:[1,0]
	v_add_f32_e32 v101, 1.0, v101
	v_rcp_f32_e32 v103, v101
	s_nop 0
	v_pk_fma_f32 v[102:103], v[102:103], 2.0, 1.0 op_sel_hi:[1,0,0] neg_lo:[1,0,0] neg_hi:[1,0,0]
	s_nop 0
	v_pk_add_f32 v[102:103], v[102:103], 1.0 op_sel_hi:[1,0]
	s_nop 0
	v_pk_mul_f32 v[94:95], v[94:95], v[102:103]
	v_lshlrev_b32_e32 v102, 16, v181
	v_and_b32_e32 v103, 0xffff0000, v181
	v_pk_fma_f32 v[96:97], v[162:163], v[102:103], v[96:97]
	v_cvt_pk_bf16_f32 v94, v94, v95
	v_mul_f32_e32 v95, 0x3d372713, v96
	v_mul_f32_e32 v95, v96, v95
	v_fma_f32 v95, v96, v95, v96
	v_mul_f32_e32 v95, 0x3f4c422a, v95
	v_add_f32_e32 v95, v95, v95
	v_mul_f32_e32 v95, 0x3fb8aa3b, v95
	v_exp_f32_e32 v95, v95
	s_nop 0
	v_add_f32_e32 v95, 1.0, v95
	v_rcp_f32_e32 v102, v95
	v_mul_f32_e32 v95, 0x3d372713, v97
	v_mul_f32_e32 v95, v97, v95
	v_fma_f32 v95, v97, v95, v97
	v_mul_f32_e32 v95, 0x3f4c422a, v95
	v_add_f32_e32 v95, v95, v95
	v_mul_f32_e32 v95, 0x3fb8aa3b, v95
	v_exp_f32_e32 v95, v95
	v_pk_mul_f32 v[96:97], v[96:97], 0.5 op_sel_hi:[1,0]
	v_add_f32_e32 v95, 1.0, v95
	v_rcp_f32_e32 v103, v95
	s_nop 0
	v_pk_fma_f32 v[102:103], v[102:103], 2.0, 1.0 op_sel_hi:[1,0,0] neg_lo:[1,0,0] neg_hi:[1,0,0]
	s_nop 0
	v_pk_add_f32 v[102:103], v[102:103], 1.0 op_sel_hi:[1,0]
	s_nop 0
	v_pk_mul_f32 v[96:97], v[96:97], v[102:103]
	s_nop 0
	v_cvt_pk_bf16_f32 v95, v96, v97
	v_add_u32_e32 v96, s0, v100
	v_ashrrev_i32_e32 v97, 31, v96
	v_lshlrev_b64 v[96:97], 10, v[96:97]
	v_lshl_add_u64 v[96:97], s[56:57], 0, v[96:97]
	v_lshl_add_u64 v[96:97], v[96:97], 0, s[22:23]
	v_lshl_add_u64 v[96:97], v[96:97], 0, v[138:139]
	global_store_dwordx2 v[96:97], v[94:95], off
	v_lshl_add_u64 v[94:95], s[28:29], 0, v[190:191]
	v_lshl_add_u64 v[94:95], v[94:95], 1, v[98:99]
	s_nop 0
	s_nop 0
	s_or_b32 s0, s28, 16
	s_ashr_i32 s0, s0, 4
	s_nop 0
	v_lshlrev_b32_e32 v104, 16, v182
	v_and_b32_e32 v105, 0xffff0000, v182
	s_nop 0
	v_pk_fma_f32 v[90:91], v[160:161], v[104:105], v[90:91]
	s_nop 0
	v_mul_f32_e32 v96, 0x3d372713, v90
	v_mul_f32_e32 v97, 0x3d372713, v91
	v_mul_f32_e32 v96, v90, v96
	v_mul_f32_e32 v97, v91, v97
	v_fma_f32 v96, v90, v96, v90
	v_fma_f32 v97, v91, v97, v91
	v_mul_f32_e32 v96, 0x3f4c422a, v96
	v_mul_f32_e32 v97, 0x3f4c422a, v97
	v_add_f32_e32 v96, v96, v96
	v_add_f32_e32 v97, v97, v97
	v_mul_f32_e32 v96, 0x3fb8aa3b, v96
	v_mul_f32_e32 v97, 0x3fb8aa3b, v97
	v_exp_f32_e32 v96, v96
	v_exp_f32_e32 v97, v97
	v_pk_mul_f32 v[90:91], v[90:91], 0.5 op_sel_hi:[1,0]
	v_add_f32_e32 v96, 1.0, v96
	v_add_f32_e32 v97, 1.0, v97
	v_rcp_f32_e32 v96, v96
	v_rcp_f32_e32 v97, v97
	s_nop 0
	v_pk_fma_f32 v[96:97], v[96:97], 2.0, 1.0 op_sel_hi:[1,0,0] neg_lo:[1,0,0] neg_hi:[1,0,0]
	s_nop 0
	v_pk_add_f32 v[96:97], v[96:97], 1.0 op_sel_hi:[1,0]
	s_nop 0
	v_pk_mul_f32 v[90:91], v[90:91], v[96:97]
	v_lshlrev_b32_e32 v96, 16, v183
	v_and_b32_e32 v97, 0xffff0000, v183
	v_pk_fma_f32 v[92:93], v[162:163], v[96:97], v[92:93]
	v_cvt_pk_bf16_f32 v90, v90, v91
	v_mul_f32_e32 v91, 0x3d372713, v92
	v_mul_f32_e32 v91, v92, v91
	v_fma_f32 v91, v92, v91, v92
	v_mul_f32_e32 v91, 0x3f4c422a, v91
	v_add_f32_e32 v91, v91, v91
	v_mul_f32_e32 v91, 0x3fb8aa3b, v91
	v_exp_f32_e32 v91, v91
	s_nop 0
	v_add_f32_e32 v91, 1.0, v91
	v_rcp_f32_e32 v96, v91
	v_mul_f32_e32 v91, 0x3d372713, v93
	v_mul_f32_e32 v91, v93, v91
	v_fma_f32 v91, v93, v91, v93
	v_mul_f32_e32 v91, 0x3f4c422a, v91
	v_add_f32_e32 v91, v91, v91
	v_mul_f32_e32 v91, 0x3fb8aa3b, v91
	v_exp_f32_e32 v91, v91
	v_pk_mul_f32 v[92:93], v[92:93], 0.5 op_sel_hi:[1,0]
	v_add_f32_e32 v91, 1.0, v91
	v_rcp_f32_e32 v97, v91
	s_nop 0
	v_pk_fma_f32 v[96:97], v[96:97], 2.0, 1.0 op_sel_hi:[1,0,0] neg_lo:[1,0,0] neg_hi:[1,0,0]
	s_nop 0
	v_pk_add_f32 v[96:97], v[96:97], 1.0 op_sel_hi:[1,0]
	s_nop 0
	v_pk_mul_f32 v[92:93], v[92:93], v[96:97]
	s_nop 0
	v_cvt_pk_bf16_f32 v91, v92, v93
	v_add_u32_e32 v92, s0, v100
	v_ashrrev_i32_e32 v93, 31, v92
	v_lshlrev_b64 v[92:93], 10, v[92:93]
	v_lshl_add_u64 v[92:93], s[56:57], 0, v[92:93]
	v_lshl_add_u64 v[92:93], v[92:93], 0, s[22:23]
	v_lshl_add_u64 v[92:93], v[92:93], 0, v[138:139]
	global_store_dwordx2 v[92:93], v[90:91], off
	s_nop 0
	s_nop 0
	s_nop 0
	s_or_b32 s0, s28, 0x80
	s_ashr_i32 s0, s0, 4
	s_nop 0
	v_lshlrev_b32_e32 v98, 16, v184
	v_and_b32_e32 v99, 0xffff0000, v184
	s_nop 0
	v_pk_fma_f32 v[86:87], v[160:161], v[98:99], v[86:87]
	s_nop 0
	v_mul_f32_e32 v90, 0x3d372713, v86
	v_mul_f32_e32 v91, 0x3d372713, v87
	v_mul_f32_e32 v90, v86, v90
	v_mul_f32_e32 v91, v87, v91
	v_fma_f32 v90, v86, v90, v86
	v_fma_f32 v91, v87, v91, v87
	v_mul_f32_e32 v90, 0x3f4c422a, v90
	v_mul_f32_e32 v91, 0x3f4c422a, v91
	v_add_f32_e32 v90, v90, v90
	v_add_f32_e32 v91, v91, v91
	v_mul_f32_e32 v90, 0x3fb8aa3b, v90
	v_mul_f32_e32 v91, 0x3fb8aa3b, v91
	v_exp_f32_e32 v90, v90
	v_exp_f32_e32 v91, v91
	v_pk_mul_f32 v[86:87], v[86:87], 0.5 op_sel_hi:[1,0]
	v_add_f32_e32 v90, 1.0, v90
	v_add_f32_e32 v91, 1.0, v91
	v_rcp_f32_e32 v90, v90
	v_rcp_f32_e32 v91, v91
	s_nop 0
	v_pk_fma_f32 v[90:91], v[90:91], 2.0, 1.0 op_sel_hi:[1,0,0] neg_lo:[1,0,0] neg_hi:[1,0,0]
	s_nop 0
	v_pk_add_f32 v[90:91], v[90:91], 1.0 op_sel_hi:[1,0]
	s_nop 0
	v_pk_mul_f32 v[86:87], v[86:87], v[90:91]
	v_lshlrev_b32_e32 v90, 16, v185
	v_and_b32_e32 v91, 0xffff0000, v185
	v_pk_fma_f32 v[88:89], v[162:163], v[90:91], v[88:89]
	v_cvt_pk_bf16_f32 v86, v86, v87
	v_mul_f32_e32 v87, 0x3d372713, v88
	v_mul_f32_e32 v87, v88, v87
	v_fma_f32 v87, v88, v87, v88
	v_mul_f32_e32 v87, 0x3f4c422a, v87
	v_add_f32_e32 v87, v87, v87
	v_mul_f32_e32 v87, 0x3fb8aa3b, v87
	v_exp_f32_e32 v87, v87
	s_nop 0
	v_add_f32_e32 v87, 1.0, v87
	v_rcp_f32_e32 v90, v87
	v_mul_f32_e32 v87, 0x3d372713, v89
	v_mul_f32_e32 v87, v89, v87
	v_fma_f32 v87, v89, v87, v89
	v_mul_f32_e32 v87, 0x3f4c422a, v87
	v_add_f32_e32 v87, v87, v87
	v_mul_f32_e32 v87, 0x3fb8aa3b, v87
	v_exp_f32_e32 v87, v87
	v_pk_mul_f32 v[88:89], v[88:89], 0.5 op_sel_hi:[1,0]
	v_add_f32_e32 v87, 1.0, v87
	v_rcp_f32_e32 v91, v87
	s_nop 0
	v_pk_fma_f32 v[90:91], v[90:91], 2.0, 1.0 op_sel_hi:[1,0,0] neg_lo:[1,0,0] neg_hi:[1,0,0]
	s_nop 0
	v_pk_add_f32 v[90:91], v[90:91], 1.0 op_sel_hi:[1,0]
	s_nop 0
	v_pk_mul_f32 v[88:89], v[88:89], v[90:91]
	s_nop 0
	v_cvt_pk_bf16_f32 v87, v88, v89
	v_add_u32_e32 v88, s0, v100
	v_ashrrev_i32_e32 v89, 31, v88
	v_lshlrev_b64 v[88:89], 10, v[88:89]
	v_lshl_add_u64 v[88:89], s[56:57], 0, v[88:89]
	v_lshl_add_u64 v[88:89], v[88:89], 0, s[22:23]
	v_lshl_add_u64 v[88:89], v[88:89], 0, v[138:139]
	global_store_dwordx2 v[88:89], v[86:87], off
	s_nop 0
	s_nop 0
	s_nop 0
	s_or_b32 s0, s28, 0x90
	s_ashr_i32 s0, s0, 4
	s_nop 0
	v_lshlrev_b32_e32 v92, 16, v186
	v_and_b32_e32 v93, 0xffff0000, v186
	s_nop 0
	v_pk_fma_f32 v[82:83], v[160:161], v[92:93], v[82:83]
	s_nop 0
	v_mul_f32_e32 v86, 0x3d372713, v82
	v_mul_f32_e32 v87, 0x3d372713, v83
	v_mul_f32_e32 v86, v82, v86
	v_mul_f32_e32 v87, v83, v87
	v_fma_f32 v86, v82, v86, v82
	v_fma_f32 v87, v83, v87, v83
	v_mul_f32_e32 v86, 0x3f4c422a, v86
	v_mul_f32_e32 v87, 0x3f4c422a, v87
	v_add_f32_e32 v86, v86, v86
	v_add_f32_e32 v87, v87, v87
	v_mul_f32_e32 v86, 0x3fb8aa3b, v86
	v_mul_f32_e32 v87, 0x3fb8aa3b, v87
	v_exp_f32_e32 v86, v86
	v_exp_f32_e32 v87, v87
	v_pk_mul_f32 v[82:83], v[82:83], 0.5 op_sel_hi:[1,0]
	v_add_f32_e32 v86, 1.0, v86
	v_add_f32_e32 v87, 1.0, v87
	v_rcp_f32_e32 v86, v86
	v_rcp_f32_e32 v87, v87
	s_nop 0
	v_pk_fma_f32 v[86:87], v[86:87], 2.0, 1.0 op_sel_hi:[1,0,0] neg_lo:[1,0,0] neg_hi:[1,0,0]
	s_nop 0
	v_pk_add_f32 v[86:87], v[86:87], 1.0 op_sel_hi:[1,0]
	s_nop 0
	v_pk_mul_f32 v[82:83], v[82:83], v[86:87]
	v_lshlrev_b32_e32 v86, 16, v187
	v_and_b32_e32 v87, 0xffff0000, v187
	v_pk_fma_f32 v[84:85], v[162:163], v[86:87], v[84:85]
	v_cvt_pk_bf16_f32 v82, v82, v83
	v_mul_f32_e32 v83, 0x3d372713, v84
	v_mul_f32_e32 v83, v84, v83
	v_fma_f32 v83, v84, v83, v84
	v_mul_f32_e32 v83, 0x3f4c422a, v83
	v_add_f32_e32 v83, v83, v83
	v_mul_f32_e32 v83, 0x3fb8aa3b, v83
	v_exp_f32_e32 v83, v83
	s_nop 0
	v_add_f32_e32 v83, 1.0, v83
	v_rcp_f32_e32 v86, v83
	v_mul_f32_e32 v83, 0x3d372713, v85
	v_mul_f32_e32 v83, v85, v83
	v_fma_f32 v83, v85, v83, v85
	v_mul_f32_e32 v83, 0x3f4c422a, v83
	v_add_f32_e32 v83, v83, v83
	v_mul_f32_e32 v83, 0x3fb8aa3b, v83
	v_exp_f32_e32 v83, v83
	v_pk_mul_f32 v[84:85], v[84:85], 0.5 op_sel_hi:[1,0]
	v_add_f32_e32 v83, 1.0, v83
	v_rcp_f32_e32 v87, v83
	s_nop 0
	v_pk_fma_f32 v[86:87], v[86:87], 2.0, 1.0 op_sel_hi:[1,0,0] neg_lo:[1,0,0] neg_hi:[1,0,0]
	s_nop 0
	v_pk_add_f32 v[86:87], v[86:87], 1.0 op_sel_hi:[1,0]
	s_nop 0
	v_pk_mul_f32 v[84:85], v[84:85], v[86:87]
	s_nop 0
	v_cvt_pk_bf16_f32 v83, v84, v85
	v_add_u32_e32 v84, s0, v100
	v_ashrrev_i32_e32 v85, 31, v84
	v_lshlrev_b64 v[84:85], 10, v[84:85]
	v_lshl_add_u64 v[84:85], s[56:57], 0, v[84:85]
	v_lshl_add_u64 v[84:85], v[84:85], 0, s[22:23]
	v_lshl_add_u64 v[84:85], v[84:85], 0, v[138:139]
	global_store_dwordx2 v[84:85], v[82:83], off
.LBB0_2603:
	s_or_b64 exec, exec, s[18:19]
	v_add3_u32 v82, s55, v146, 48
	s_movk_i32 s0, 0x210
	v_cmp_gt_i32_e32 vcc, s0, v82
	s_and_saveexec_b64 s[18:19], vcc
	s_cbranch_execz .LBB0_2605
	v_readlane_b32 s22, v246, 9
	v_ashrrev_i32_e32 v83, 31, v82
	v_readlane_b32 s23, v246, 10
	v_lshl_add_u64 v[86:87], s[16:17], 0, v[82:83]
	v_lshlrev_b32_e32 v84, 5, v82
	v_readlane_b32 s0, v246, 49
	v_mov_b64_e32 v[82:83], s[22:23]
	s_movk_i32 s20, 0x600
	s_lshl_b32 s0, s0, 8
	v_mad_u64_u32 v[82:83], s[22:23], v86, s20, v[82:83]
	s_or_b32 s28, s0, s47
	v_mov_b32_e32 v86, v83
	v_or_b32_e32 v88, s28, v190
	v_mad_u64_u32 v[86:87], s[22:23], v87, s20, v[86:87]
	s_ashr_i32 s0, s28, 4
	v_mov_b32_e32 v83, v86
	v_ashrrev_i32_e32 v89, 31, v88
	s_lshl_b64 s[22:23], s[14:15], 2
	v_lshl_add_u64 v[86:87], v[88:89], 1, v[82:83]
	s_add_u32 s44, s48, s22
	s_nop 0
	s_addc_u32 s45, s49, s23
	s_nop 0
	v_readlane_b32 s56, v246, 17
	v_readlane_b32 s57, v246, 18
	s_lshl_b64 s[22:23], s[14:15], 1
	v_mov_b32_e32 v139, v191
	s_ashr_i32 s29, s28, 31
	s_nop 0
	v_lshlrev_b32_e32 v92, 16, v188
	v_and_b32_e32 v93, 0xffff0000, v188
	v_pk_fma_f32 v[78:79], v[160:161], v[92:93], v[78:79]
	s_nop 0
	v_mul_f32_e32 v85, 0x3d372713, v78
	v_mul_f32_e32 v85, v78, v85
	v_fma_f32 v85, v78, v85, v78
	v_mul_f32_e32 v85, 0x3f4c422a, v85
	v_add_f32_e32 v85, v85, v85
	v_mul_f32_e32 v85, 0x3fb8aa3b, v85
	v_exp_f32_e32 v85, v85
	s_nop 0
	v_add_f32_e32 v85, 1.0, v85
	v_rcp_f32_e32 v86, v85
	v_mul_f32_e32 v85, 0x3d372713, v79
	v_mul_f32_e32 v85, v79, v85
	v_fma_f32 v85, v79, v85, v79
	v_mul_f32_e32 v85, 0x3f4c422a, v85
	v_add_f32_e32 v85, v85, v85
	v_mul_f32_e32 v85, 0x3fb8aa3b, v85
	v_exp_f32_e32 v85, v85
	v_pk_mul_f32 v[78:79], v[78:79], 0.5 op_sel_hi:[1,0]
	v_add_f32_e32 v85, 1.0, v85
	v_rcp_f32_e32 v87, v85
	s_nop 0
	v_pk_fma_f32 v[86:87], v[86:87], 2.0, 1.0 op_sel_hi:[1,0,0] neg_lo:[1,0,0] neg_hi:[1,0,0]
	s_nop 0
	v_pk_add_f32 v[86:87], v[86:87], 1.0 op_sel_hi:[1,0]
	s_nop 0
	v_pk_mul_f32 v[78:79], v[78:79], v[86:87]
	v_lshlrev_b32_e32 v86, 16, v189
	v_and_b32_e32 v87, 0xffff0000, v189
	v_pk_fma_f32 v[80:81], v[162:163], v[86:87], v[80:81]
	v_cvt_pk_bf16_f32 v78, v78, v79
	v_mul_f32_e32 v79, 0x3d372713, v80
	v_mul_f32_e32 v79, v80, v79
	v_fma_f32 v79, v80, v79, v80
	v_mul_f32_e32 v79, 0x3f4c422a, v79
	v_add_f32_e32 v79, v79, v79
	v_mul_f32_e32 v79, 0x3fb8aa3b, v79
	v_exp_f32_e32 v79, v79
	s_nop 0
	v_add_f32_e32 v79, 1.0, v79
	v_rcp_f32_e32 v86, v79
	v_mul_f32_e32 v79, 0x3d372713, v81
	v_mul_f32_e32 v79, v81, v79
	v_fma_f32 v79, v81, v79, v81
	v_mul_f32_e32 v79, 0x3f4c422a, v79
	v_add_f32_e32 v79, v79, v79
	v_mul_f32_e32 v79, 0x3fb8aa3b, v79
	v_exp_f32_e32 v79, v79
	v_pk_mul_f32 v[80:81], v[80:81], 0.5 op_sel_hi:[1,0]
	v_add_f32_e32 v79, 1.0, v79
	v_rcp_f32_e32 v87, v79
	s_nop 0
	v_pk_fma_f32 v[86:87], v[86:87], 2.0, 1.0 op_sel_hi:[1,0,0] neg_lo:[1,0,0] neg_hi:[1,0,0]
	s_nop 0
	v_pk_add_f32 v[86:87], v[86:87], 1.0 op_sel_hi:[1,0]
	s_nop 0
	v_pk_mul_f32 v[80:81], v[80:81], v[86:87]
	s_nop 0
	v_cvt_pk_bf16_f32 v79, v80, v81
	v_add_u32_e32 v80, s0, v84
	v_ashrrev_i32_e32 v81, 31, v80
	v_lshlrev_b64 v[80:81], 10, v[80:81]
	v_lshl_add_u64 v[80:81], s[56:57], 0, v[80:81]
	v_lshl_add_u64 v[80:81], v[80:81], 0, s[22:23]
	v_lshl_add_u64 v[80:81], v[80:81], 0, v[138:139]
	global_store_dwordx2 v[80:81], v[78:79], off
	v_lshl_add_u64 v[78:79], s[28:29], 0, v[190:191]
	v_lshl_add_u64 v[78:79], v[78:79], 1, v[82:83]
	s_nop 0
	s_nop 0
	s_or_b32 s0, s28, 16
	s_ashr_i32 s0, s0, 4
	s_nop 0
	v_lshlrev_b32_e32 v88, 16, v192
	v_and_b32_e32 v89, 0xffff0000, v192
	s_nop 0
	v_pk_fma_f32 v[74:75], v[160:161], v[88:89], v[74:75]
	s_nop 0
	v_mul_f32_e32 v80, 0x3d372713, v74
	v_mul_f32_e32 v81, 0x3d372713, v75
	v_mul_f32_e32 v80, v74, v80
	v_mul_f32_e32 v81, v75, v81
	v_fma_f32 v80, v74, v80, v74
	v_fma_f32 v81, v75, v81, v75
	v_mul_f32_e32 v80, 0x3f4c422a, v80
	v_mul_f32_e32 v81, 0x3f4c422a, v81
	v_add_f32_e32 v80, v80, v80
	v_add_f32_e32 v81, v81, v81
	v_mul_f32_e32 v80, 0x3fb8aa3b, v80
	v_mul_f32_e32 v81, 0x3fb8aa3b, v81
	v_exp_f32_e32 v80, v80
	v_exp_f32_e32 v81, v81
	v_pk_mul_f32 v[74:75], v[74:75], 0.5 op_sel_hi:[1,0]
	v_add_f32_e32 v80, 1.0, v80
	v_add_f32_e32 v81, 1.0, v81
	v_rcp_f32_e32 v80, v80
	v_rcp_f32_e32 v81, v81
	s_nop 0
	v_pk_fma_f32 v[80:81], v[80:81], 2.0, 1.0 op_sel_hi:[1,0,0] neg_lo:[1,0,0] neg_hi:[1,0,0]
	s_nop 0
	v_pk_add_f32 v[80:81], v[80:81], 1.0 op_sel_hi:[1,0]
	s_nop 0
	v_pk_mul_f32 v[74:75], v[74:75], v[80:81]
	v_lshlrev_b32_e32 v80, 16, v193
	v_and_b32_e32 v81, 0xffff0000, v193
	v_pk_fma_f32 v[76:77], v[162:163], v[80:81], v[76:77]
	v_cvt_pk_bf16_f32 v74, v74, v75
	v_mul_f32_e32 v75, 0x3d372713, v76
	v_mul_f32_e32 v75, v76, v75
	v_fma_f32 v75, v76, v75, v76
	v_mul_f32_e32 v75, 0x3f4c422a, v75
	v_add_f32_e32 v75, v75, v75
	v_mul_f32_e32 v75, 0x3fb8aa3b, v75
	v_exp_f32_e32 v75, v75
	s_nop 0
	v_add_f32_e32 v75, 1.0, v75
	v_rcp_f32_e32 v80, v75
	v_mul_f32_e32 v75, 0x3d372713, v77
	v_mul_f32_e32 v75, v77, v75
	v_fma_f32 v75, v77, v75, v77
	v_mul_f32_e32 v75, 0x3f4c422a, v75
	v_add_f32_e32 v75, v75, v75
	v_mul_f32_e32 v75, 0x3fb8aa3b, v75
	v_exp_f32_e32 v75, v75
	v_pk_mul_f32 v[76:77], v[76:77], 0.5 op_sel_hi:[1,0]
	v_add_f32_e32 v75, 1.0, v75
	v_rcp_f32_e32 v81, v75
	s_nop 0
	v_pk_fma_f32 v[80:81], v[80:81], 2.0, 1.0 op_sel_hi:[1,0,0] neg_lo:[1,0,0] neg_hi:[1,0,0]
	s_nop 0
	v_pk_add_f32 v[80:81], v[80:81], 1.0 op_sel_hi:[1,0]
	s_nop 0
	v_pk_mul_f32 v[76:77], v[76:77], v[80:81]
	s_nop 0
	v_cvt_pk_bf16_f32 v75, v76, v77
	v_add_u32_e32 v76, s0, v84
	v_ashrrev_i32_e32 v77, 31, v76
	v_lshlrev_b64 v[76:77], 10, v[76:77]
	v_lshl_add_u64 v[76:77], s[56:57], 0, v[76:77]
	v_lshl_add_u64 v[76:77], v[76:77], 0, s[22:23]
	v_lshl_add_u64 v[76:77], v[76:77], 0, v[138:139]
	global_store_dwordx2 v[76:77], v[74:75], off
	s_nop 0
	s_nop 0
	s_nop 0
	s_or_b32 s0, s28, 0x80
	s_ashr_i32 s0, s0, 4
	s_nop 0
	v_lshlrev_b32_e32 v82, 16, v194
	v_and_b32_e32 v83, 0xffff0000, v194
	s_nop 0
	v_pk_fma_f32 v[70:71], v[160:161], v[82:83], v[70:71]
	s_nop 0
	v_mul_f32_e32 v74, 0x3d372713, v70
	v_mul_f32_e32 v75, 0x3d372713, v71
	v_mul_f32_e32 v74, v70, v74
	v_mul_f32_e32 v75, v71, v75
	v_fma_f32 v74, v70, v74, v70
	v_fma_f32 v75, v71, v75, v71
	v_mul_f32_e32 v74, 0x3f4c422a, v74
	v_mul_f32_e32 v75, 0x3f4c422a, v75
	v_add_f32_e32 v74, v74, v74
	v_add_f32_e32 v75, v75, v75
	v_mul_f32_e32 v74, 0x3fb8aa3b, v74
	v_mul_f32_e32 v75, 0x3fb8aa3b, v75
	v_exp_f32_e32 v74, v74
	v_exp_f32_e32 v75, v75
	v_pk_mul_f32 v[70:71], v[70:71], 0.5 op_sel_hi:[1,0]
	v_add_f32_e32 v74, 1.0, v74
	v_add_f32_e32 v75, 1.0, v75
	v_rcp_f32_e32 v74, v74
	v_rcp_f32_e32 v75, v75
	s_nop 0
	v_pk_fma_f32 v[74:75], v[74:75], 2.0, 1.0 op_sel_hi:[1,0,0] neg_lo:[1,0,0] neg_hi:[1,0,0]
	s_nop 0
	v_pk_add_f32 v[74:75], v[74:75], 1.0 op_sel_hi:[1,0]
	s_nop 0
	v_pk_mul_f32 v[70:71], v[70:71], v[74:75]
	v_lshlrev_b32_e32 v74, 16, v195
	v_and_b32_e32 v75, 0xffff0000, v195
	v_pk_fma_f32 v[72:73], v[162:163], v[74:75], v[72:73]
	v_cvt_pk_bf16_f32 v70, v70, v71
	v_mul_f32_e32 v71, 0x3d372713, v72
	v_mul_f32_e32 v71, v72, v71
	v_fma_f32 v71, v72, v71, v72
	v_mul_f32_e32 v71, 0x3f4c422a, v71
	v_add_f32_e32 v71, v71, v71
	v_mul_f32_e32 v71, 0x3fb8aa3b, v71
	v_exp_f32_e32 v71, v71
	s_nop 0
	v_add_f32_e32 v71, 1.0, v71
	v_rcp_f32_e32 v74, v71
	v_mul_f32_e32 v71, 0x3d372713, v73
	v_mul_f32_e32 v71, v73, v71
	v_fma_f32 v71, v73, v71, v73
	v_mul_f32_e32 v71, 0x3f4c422a, v71
	v_add_f32_e32 v71, v71, v71
	v_mul_f32_e32 v71, 0x3fb8aa3b, v71
	v_exp_f32_e32 v71, v71
	v_pk_mul_f32 v[72:73], v[72:73], 0.5 op_sel_hi:[1,0]
	v_add_f32_e32 v71, 1.0, v71
	v_rcp_f32_e32 v75, v71
	s_nop 0
	v_pk_fma_f32 v[74:75], v[74:75], 2.0, 1.0 op_sel_hi:[1,0,0] neg_lo:[1,0,0] neg_hi:[1,0,0]
	s_nop 0
	v_pk_add_f32 v[74:75], v[74:75], 1.0 op_sel_hi:[1,0]
	s_nop 0
	v_pk_mul_f32 v[72:73], v[72:73], v[74:75]
	s_nop 0
	v_cvt_pk_bf16_f32 v71, v72, v73
	v_add_u32_e32 v72, s0, v84
	v_ashrrev_i32_e32 v73, 31, v72
	v_lshlrev_b64 v[72:73], 10, v[72:73]
	v_lshl_add_u64 v[72:73], s[56:57], 0, v[72:73]
	v_lshl_add_u64 v[72:73], v[72:73], 0, s[22:23]
	v_lshl_add_u64 v[72:73], v[72:73], 0, v[138:139]
	global_store_dwordx2 v[72:73], v[70:71], off
	s_nop 0
	s_nop 0
	s_nop 0
	s_or_b32 s0, s28, 0x90
	s_ashr_i32 s0, s0, 4
	s_nop 0
	v_lshlrev_b32_e32 v76, 16, v196
	v_and_b32_e32 v77, 0xffff0000, v196
	s_nop 0
	v_pk_fma_f32 v[66:67], v[160:161], v[76:77], v[66:67]
	s_nop 0
	v_mul_f32_e32 v70, 0x3d372713, v66
	v_mul_f32_e32 v71, 0x3d372713, v67
	v_mul_f32_e32 v70, v66, v70
	v_mul_f32_e32 v71, v67, v71
	v_fma_f32 v70, v66, v70, v66
	v_fma_f32 v71, v67, v71, v67
	v_mul_f32_e32 v70, 0x3f4c422a, v70
	v_mul_f32_e32 v71, 0x3f4c422a, v71
	v_add_f32_e32 v70, v70, v70
	v_add_f32_e32 v71, v71, v71
	v_mul_f32_e32 v70, 0x3fb8aa3b, v70
	v_mul_f32_e32 v71, 0x3fb8aa3b, v71
	v_exp_f32_e32 v70, v70
	v_exp_f32_e32 v71, v71
	v_pk_mul_f32 v[66:67], v[66:67], 0.5 op_sel_hi:[1,0]
	v_add_f32_e32 v70, 1.0, v70
	v_add_f32_e32 v71, 1.0, v71
	v_rcp_f32_e32 v70, v70
	v_rcp_f32_e32 v71, v71
	s_nop 0
	v_pk_fma_f32 v[70:71], v[70:71], 2.0, 1.0 op_sel_hi:[1,0,0] neg_lo:[1,0,0] neg_hi:[1,0,0]
	s_nop 0
	v_pk_add_f32 v[70:71], v[70:71], 1.0 op_sel_hi:[1,0]
	s_nop 0
	v_pk_mul_f32 v[66:67], v[66:67], v[70:71]
	v_lshlrev_b32_e32 v70, 16, v197
	v_and_b32_e32 v71, 0xffff0000, v197
	v_pk_fma_f32 v[68:69], v[162:163], v[70:71], v[68:69]
	v_cvt_pk_bf16_f32 v66, v66, v67
	v_mul_f32_e32 v67, 0x3d372713, v68
	v_mul_f32_e32 v67, v68, v67
	v_fma_f32 v67, v68, v67, v68
	v_mul_f32_e32 v67, 0x3f4c422a, v67
	v_add_f32_e32 v67, v67, v67
	v_mul_f32_e32 v67, 0x3fb8aa3b, v67
	v_exp_f32_e32 v67, v67
	s_nop 0
	v_add_f32_e32 v67, 1.0, v67
	v_rcp_f32_e32 v70, v67
	v_mul_f32_e32 v67, 0x3d372713, v69
	v_mul_f32_e32 v67, v69, v67
	v_fma_f32 v67, v69, v67, v69
	v_mul_f32_e32 v67, 0x3f4c422a, v67
	v_add_f32_e32 v67, v67, v67
	v_mul_f32_e32 v67, 0x3fb8aa3b, v67
	v_exp_f32_e32 v67, v67
	v_pk_mul_f32 v[68:69], v[68:69], 0.5 op_sel_hi:[1,0]
	v_add_f32_e32 v67, 1.0, v67
	v_rcp_f32_e32 v71, v67
	s_nop 0
	v_pk_fma_f32 v[70:71], v[70:71], 2.0, 1.0 op_sel_hi:[1,0,0] neg_lo:[1,0,0] neg_hi:[1,0,0]
	s_nop 0
	v_pk_add_f32 v[70:71], v[70:71], 1.0 op_sel_hi:[1,0]
	s_nop 0
	v_pk_mul_f32 v[68:69], v[68:69], v[70:71]
	s_nop 0
	v_cvt_pk_bf16_f32 v67, v68, v69
	v_add_u32_e32 v68, s0, v84
	v_ashrrev_i32_e32 v69, 31, v68
	v_lshlrev_b64 v[68:69], 10, v[68:69]
	v_lshl_add_u64 v[68:69], s[56:57], 0, v[68:69]
	v_lshl_add_u64 v[68:69], v[68:69], 0, s[22:23]
	v_lshl_add_u64 v[68:69], v[68:69], 0, v[138:139]
	global_store_dwordx2 v[68:69], v[66:67], off
.LBB0_2605:
	s_or_b64 exec, exec, s[18:19]
	v_add_u32_e32 v66, 0x80, v140
	s_movk_i32 s0, 0x210
	v_cmp_gt_i32_e32 vcc, s0, v66
	s_and_saveexec_b64 s[18:19], vcc
	s_cbranch_execz .LBB0_2607
	v_readlane_b32 s22, v246, 9
	v_ashrrev_i32_e32 v67, 31, v66
	v_readlane_b32 s23, v246, 10
	v_lshl_add_u64 v[70:71], s[16:17], 0, v[66:67]
	v_lshlrev_b32_e32 v68, 5, v66
	v_readlane_b32 s0, v246, 49
	v_mov_b64_e32 v[66:67], s[22:23]
	s_movk_i32 s20, 0x600
	s_lshl_b32 s0, s0, 8
	v_mad_u64_u32 v[66:67], s[22:23], v70, s20, v[66:67]
	s_or_b32 s28, s0, s47
	v_mov_b32_e32 v70, v67
	v_or_b32_e32 v72, s28, v190
	v_mad_u64_u32 v[70:71], s[22:23], v71, s20, v[70:71]
	s_ashr_i32 s0, s28, 4
	v_mov_b32_e32 v67, v70
	v_ashrrev_i32_e32 v73, 31, v72
	s_lshl_b64 s[22:23], s[14:15], 2
	v_lshl_add_u64 v[70:71], v[72:73], 1, v[66:67]
	s_add_u32 s44, s48, s22
	s_nop 0
	s_addc_u32 s45, s49, s23
	s_nop 0
	v_readlane_b32 s56, v246, 17
	v_readlane_b32 s57, v246, 18
	s_lshl_b64 s[22:23], s[14:15], 1
	v_mov_b32_e32 v139, v191
	s_ashr_i32 s29, s28, 31
	s_nop 0
	v_lshlrev_b32_e32 v76, 16, v198
	v_and_b32_e32 v77, 0xffff0000, v198
	v_pk_fma_f32 v[62:63], v[160:161], v[76:77], v[62:63]
	s_nop 0
	v_mul_f32_e32 v69, 0x3d372713, v62
	v_mul_f32_e32 v69, v62, v69
	v_fma_f32 v69, v62, v69, v62
	v_mul_f32_e32 v69, 0x3f4c422a, v69
	v_add_f32_e32 v69, v69, v69
	v_mul_f32_e32 v69, 0x3fb8aa3b, v69
	v_exp_f32_e32 v69, v69
	s_nop 0
	v_add_f32_e32 v69, 1.0, v69
	v_rcp_f32_e32 v70, v69
	v_mul_f32_e32 v69, 0x3d372713, v63
	v_mul_f32_e32 v69, v63, v69
	v_fma_f32 v69, v63, v69, v63
	v_mul_f32_e32 v69, 0x3f4c422a, v69
	v_add_f32_e32 v69, v69, v69
	v_mul_f32_e32 v69, 0x3fb8aa3b, v69
	v_exp_f32_e32 v69, v69
	v_pk_mul_f32 v[62:63], v[62:63], 0.5 op_sel_hi:[1,0]
	v_add_f32_e32 v69, 1.0, v69
	v_rcp_f32_e32 v71, v69
	s_nop 0
	v_pk_fma_f32 v[70:71], v[70:71], 2.0, 1.0 op_sel_hi:[1,0,0] neg_lo:[1,0,0] neg_hi:[1,0,0]
	s_nop 0
	v_pk_add_f32 v[70:71], v[70:71], 1.0 op_sel_hi:[1,0]
	s_nop 0
	v_pk_mul_f32 v[62:63], v[62:63], v[70:71]
	v_lshlrev_b32_e32 v70, 16, v199
	v_and_b32_e32 v71, 0xffff0000, v199
	v_pk_fma_f32 v[64:65], v[162:163], v[70:71], v[64:65]
	v_cvt_pk_bf16_f32 v62, v62, v63
	v_mul_f32_e32 v63, 0x3d372713, v64
	v_mul_f32_e32 v63, v64, v63
	v_fma_f32 v63, v64, v63, v64
	v_mul_f32_e32 v63, 0x3f4c422a, v63
	v_add_f32_e32 v63, v63, v63
	v_mul_f32_e32 v63, 0x3fb8aa3b, v63
	v_exp_f32_e32 v63, v63
	s_nop 0
	v_add_f32_e32 v63, 1.0, v63
	v_rcp_f32_e32 v70, v63
	v_mul_f32_e32 v63, 0x3d372713, v65
	v_mul_f32_e32 v63, v65, v63
	v_fma_f32 v63, v65, v63, v65
	v_mul_f32_e32 v63, 0x3f4c422a, v63
	v_add_f32_e32 v63, v63, v63
	v_mul_f32_e32 v63, 0x3fb8aa3b, v63
	v_exp_f32_e32 v63, v63
	v_pk_mul_f32 v[64:65], v[64:65], 0.5 op_sel_hi:[1,0]
	v_add_f32_e32 v63, 1.0, v63
	v_rcp_f32_e32 v71, v63
	s_nop 0
	v_pk_fma_f32 v[70:71], v[70:71], 2.0, 1.0 op_sel_hi:[1,0,0] neg_lo:[1,0,0] neg_hi:[1,0,0]
	s_nop 0
	v_pk_add_f32 v[70:71], v[70:71], 1.0 op_sel_hi:[1,0]
	s_nop 0
	v_pk_mul_f32 v[64:65], v[64:65], v[70:71]
	s_nop 0
	v_cvt_pk_bf16_f32 v63, v64, v65
	v_add_u32_e32 v64, s0, v68
	v_ashrrev_i32_e32 v65, 31, v64
	v_lshlrev_b64 v[64:65], 10, v[64:65]
	v_lshl_add_u64 v[64:65], s[56:57], 0, v[64:65]
	v_lshl_add_u64 v[64:65], v[64:65], 0, s[22:23]
	v_lshl_add_u64 v[64:65], v[64:65], 0, v[138:139]
	global_store_dwordx2 v[64:65], v[62:63], off
	v_lshl_add_u64 v[62:63], s[28:29], 0, v[190:191]
	v_lshl_add_u64 v[62:63], v[62:63], 1, v[66:67]
	s_nop 0
	s_nop 0
	s_or_b32 s0, s28, 16
	s_ashr_i32 s0, s0, 4
	s_nop 0
	v_lshlrev_b32_e32 v72, 16, v200
	v_and_b32_e32 v73, 0xffff0000, v200
	s_nop 0
	v_pk_fma_f32 v[58:59], v[160:161], v[72:73], v[58:59]
	s_nop 0
	v_mul_f32_e32 v64, 0x3d372713, v58
	v_mul_f32_e32 v65, 0x3d372713, v59
	v_mul_f32_e32 v64, v58, v64
	v_mul_f32_e32 v65, v59, v65
	v_fma_f32 v64, v58, v64, v58
	v_fma_f32 v65, v59, v65, v59
	v_mul_f32_e32 v64, 0x3f4c422a, v64
	v_mul_f32_e32 v65, 0x3f4c422a, v65
	v_add_f32_e32 v64, v64, v64
	v_add_f32_e32 v65, v65, v65
	v_mul_f32_e32 v64, 0x3fb8aa3b, v64
	v_mul_f32_e32 v65, 0x3fb8aa3b, v65
	v_exp_f32_e32 v64, v64
	v_exp_f32_e32 v65, v65
	v_pk_mul_f32 v[58:59], v[58:59], 0.5 op_sel_hi:[1,0]
	v_add_f32_e32 v64, 1.0, v64
	v_add_f32_e32 v65, 1.0, v65
	v_rcp_f32_e32 v64, v64
	v_rcp_f32_e32 v65, v65
	s_nop 0
	v_pk_fma_f32 v[64:65], v[64:65], 2.0, 1.0 op_sel_hi:[1,0,0] neg_lo:[1,0,0] neg_hi:[1,0,0]
	s_nop 0
	v_pk_add_f32 v[64:65], v[64:65], 1.0 op_sel_hi:[1,0]
	s_nop 0
	v_pk_mul_f32 v[58:59], v[58:59], v[64:65]
	v_lshlrev_b32_e32 v64, 16, v201
	v_and_b32_e32 v65, 0xffff0000, v201
	v_pk_fma_f32 v[60:61], v[162:163], v[64:65], v[60:61]
	v_cvt_pk_bf16_f32 v58, v58, v59
	v_mul_f32_e32 v59, 0x3d372713, v60
	v_mul_f32_e32 v59, v60, v59
	v_fma_f32 v59, v60, v59, v60
	v_mul_f32_e32 v59, 0x3f4c422a, v59
	v_add_f32_e32 v59, v59, v59
	v_mul_f32_e32 v59, 0x3fb8aa3b, v59
	v_exp_f32_e32 v59, v59
	s_nop 0
	v_add_f32_e32 v59, 1.0, v59
	v_rcp_f32_e32 v64, v59
	v_mul_f32_e32 v59, 0x3d372713, v61
	v_mul_f32_e32 v59, v61, v59
	v_fma_f32 v59, v61, v59, v61
	v_mul_f32_e32 v59, 0x3f4c422a, v59
	v_add_f32_e32 v59, v59, v59
	v_mul_f32_e32 v59, 0x3fb8aa3b, v59
	v_exp_f32_e32 v59, v59
	v_pk_mul_f32 v[60:61], v[60:61], 0.5 op_sel_hi:[1,0]
	v_add_f32_e32 v59, 1.0, v59
	v_rcp_f32_e32 v65, v59
	s_nop 0
	v_pk_fma_f32 v[64:65], v[64:65], 2.0, 1.0 op_sel_hi:[1,0,0] neg_lo:[1,0,0] neg_hi:[1,0,0]
	s_nop 0
	v_pk_add_f32 v[64:65], v[64:65], 1.0 op_sel_hi:[1,0]
	s_nop 0
	v_pk_mul_f32 v[60:61], v[60:61], v[64:65]
	s_nop 0
	v_cvt_pk_bf16_f32 v59, v60, v61
	v_add_u32_e32 v60, s0, v68
	v_ashrrev_i32_e32 v61, 31, v60
	v_lshlrev_b64 v[60:61], 10, v[60:61]
	v_lshl_add_u64 v[60:61], s[56:57], 0, v[60:61]
	v_lshl_add_u64 v[60:61], v[60:61], 0, s[22:23]
	v_lshl_add_u64 v[60:61], v[60:61], 0, v[138:139]
	global_store_dwordx2 v[60:61], v[58:59], off
	s_nop 0
	s_nop 0
	s_nop 0
	s_or_b32 s0, s28, 0x80
	s_ashr_i32 s0, s0, 4
	s_nop 0
	v_lshlrev_b32_e32 v66, 16, v202
	v_and_b32_e32 v67, 0xffff0000, v202
	s_nop 0
	v_pk_fma_f32 v[54:55], v[160:161], v[66:67], v[54:55]
	s_nop 0
	v_mul_f32_e32 v58, 0x3d372713, v54
	v_mul_f32_e32 v59, 0x3d372713, v55
	v_mul_f32_e32 v58, v54, v58
	v_mul_f32_e32 v59, v55, v59
	v_fma_f32 v58, v54, v58, v54
	v_fma_f32 v59, v55, v59, v55
	v_mul_f32_e32 v58, 0x3f4c422a, v58
	v_mul_f32_e32 v59, 0x3f4c422a, v59
	v_add_f32_e32 v58, v58, v58
	v_add_f32_e32 v59, v59, v59
	v_mul_f32_e32 v58, 0x3fb8aa3b, v58
	v_mul_f32_e32 v59, 0x3fb8aa3b, v59
	v_exp_f32_e32 v58, v58
	v_exp_f32_e32 v59, v59
	v_pk_mul_f32 v[54:55], v[54:55], 0.5 op_sel_hi:[1,0]
	v_add_f32_e32 v58, 1.0, v58
	v_add_f32_e32 v59, 1.0, v59
	v_rcp_f32_e32 v58, v58
	v_rcp_f32_e32 v59, v59
	s_nop 0
	v_pk_fma_f32 v[58:59], v[58:59], 2.0, 1.0 op_sel_hi:[1,0,0] neg_lo:[1,0,0] neg_hi:[1,0,0]
	s_nop 0
	v_pk_add_f32 v[58:59], v[58:59], 1.0 op_sel_hi:[1,0]
	s_nop 0
	v_pk_mul_f32 v[54:55], v[54:55], v[58:59]
	v_lshlrev_b32_e32 v58, 16, v203
	v_and_b32_e32 v59, 0xffff0000, v203
	v_pk_fma_f32 v[56:57], v[162:163], v[58:59], v[56:57]
	v_cvt_pk_bf16_f32 v54, v54, v55
	v_mul_f32_e32 v55, 0x3d372713, v56
	v_mul_f32_e32 v55, v56, v55
	v_fma_f32 v55, v56, v55, v56
	v_mul_f32_e32 v55, 0x3f4c422a, v55
	v_add_f32_e32 v55, v55, v55
	v_mul_f32_e32 v55, 0x3fb8aa3b, v55
	v_exp_f32_e32 v55, v55
	s_nop 0
	v_add_f32_e32 v55, 1.0, v55
	v_rcp_f32_e32 v58, v55
	v_mul_f32_e32 v55, 0x3d372713, v57
	v_mul_f32_e32 v55, v57, v55
	v_fma_f32 v55, v57, v55, v57
	v_mul_f32_e32 v55, 0x3f4c422a, v55
	v_add_f32_e32 v55, v55, v55
	v_mul_f32_e32 v55, 0x3fb8aa3b, v55
	v_exp_f32_e32 v55, v55
	v_pk_mul_f32 v[56:57], v[56:57], 0.5 op_sel_hi:[1,0]
	v_add_f32_e32 v55, 1.0, v55
	v_rcp_f32_e32 v59, v55
	s_nop 0
	v_pk_fma_f32 v[58:59], v[58:59], 2.0, 1.0 op_sel_hi:[1,0,0] neg_lo:[1,0,0] neg_hi:[1,0,0]
	s_nop 0
	v_pk_add_f32 v[58:59], v[58:59], 1.0 op_sel_hi:[1,0]
	s_nop 0
	v_pk_mul_f32 v[56:57], v[56:57], v[58:59]
	s_nop 0
	v_cvt_pk_bf16_f32 v55, v56, v57
	v_add_u32_e32 v56, s0, v68
	v_ashrrev_i32_e32 v57, 31, v56
	v_lshlrev_b64 v[56:57], 10, v[56:57]
	v_lshl_add_u64 v[56:57], s[56:57], 0, v[56:57]
	v_lshl_add_u64 v[56:57], v[56:57], 0, s[22:23]
	v_lshl_add_u64 v[56:57], v[56:57], 0, v[138:139]
	global_store_dwordx2 v[56:57], v[54:55], off
	s_nop 0
	s_nop 0
	s_nop 0
	s_or_b32 s0, s28, 0x90
	s_ashr_i32 s0, s0, 4
	s_nop 0
	v_lshlrev_b32_e32 v60, 16, v204
	v_and_b32_e32 v61, 0xffff0000, v204
	s_nop 0
	v_pk_fma_f32 v[50:51], v[160:161], v[60:61], v[50:51]
	s_nop 0
	v_mul_f32_e32 v54, 0x3d372713, v50
	v_mul_f32_e32 v55, 0x3d372713, v51
	v_mul_f32_e32 v54, v50, v54
	v_mul_f32_e32 v55, v51, v55
	v_fma_f32 v54, v50, v54, v50
	v_fma_f32 v55, v51, v55, v51
	v_mul_f32_e32 v54, 0x3f4c422a, v54
	v_mul_f32_e32 v55, 0x3f4c422a, v55
	v_add_f32_e32 v54, v54, v54
	v_add_f32_e32 v55, v55, v55
	v_mul_f32_e32 v54, 0x3fb8aa3b, v54
	v_mul_f32_e32 v55, 0x3fb8aa3b, v55
	v_exp_f32_e32 v54, v54
	v_exp_f32_e32 v55, v55
	v_pk_mul_f32 v[50:51], v[50:51], 0.5 op_sel_hi:[1,0]
	v_add_f32_e32 v54, 1.0, v54
	v_add_f32_e32 v55, 1.0, v55
	v_rcp_f32_e32 v54, v54
	v_rcp_f32_e32 v55, v55
	s_nop 0
	v_pk_fma_f32 v[54:55], v[54:55], 2.0, 1.0 op_sel_hi:[1,0,0] neg_lo:[1,0,0] neg_hi:[1,0,0]
	s_nop 0
	v_pk_add_f32 v[54:55], v[54:55], 1.0 op_sel_hi:[1,0]
	s_nop 0
	v_pk_mul_f32 v[50:51], v[50:51], v[54:55]
	v_lshlrev_b32_e32 v54, 16, v205
	v_and_b32_e32 v55, 0xffff0000, v205
	v_pk_fma_f32 v[52:53], v[162:163], v[54:55], v[52:53]
	v_cvt_pk_bf16_f32 v50, v50, v51
	v_mul_f32_e32 v51, 0x3d372713, v52
	v_mul_f32_e32 v51, v52, v51
	v_fma_f32 v51, v52, v51, v52
	v_mul_f32_e32 v51, 0x3f4c422a, v51
	v_add_f32_e32 v51, v51, v51
	v_mul_f32_e32 v51, 0x3fb8aa3b, v51
	v_exp_f32_e32 v51, v51
	s_nop 0
	v_add_f32_e32 v51, 1.0, v51
	v_rcp_f32_e32 v54, v51
	v_mul_f32_e32 v51, 0x3d372713, v53
	v_mul_f32_e32 v51, v53, v51
	v_fma_f32 v51, v53, v51, v53
	v_mul_f32_e32 v51, 0x3f4c422a, v51
	v_add_f32_e32 v51, v51, v51
	v_mul_f32_e32 v51, 0x3fb8aa3b, v51
	v_exp_f32_e32 v51, v51
	v_pk_mul_f32 v[52:53], v[52:53], 0.5 op_sel_hi:[1,0]
	v_add_f32_e32 v51, 1.0, v51
	v_rcp_f32_e32 v55, v51
	s_nop 0
	v_pk_fma_f32 v[54:55], v[54:55], 2.0, 1.0 op_sel_hi:[1,0,0] neg_lo:[1,0,0] neg_hi:[1,0,0]
	s_nop 0
	v_pk_add_f32 v[54:55], v[54:55], 1.0 op_sel_hi:[1,0]
	s_nop 0
	v_pk_mul_f32 v[52:53], v[52:53], v[54:55]
	s_nop 0
	v_cvt_pk_bf16_f32 v51, v52, v53
	v_add_u32_e32 v52, s0, v68
	v_ashrrev_i32_e32 v53, 31, v52
	v_lshlrev_b64 v[52:53], 10, v[52:53]
	v_lshl_add_u64 v[52:53], s[56:57], 0, v[52:53]
	v_lshl_add_u64 v[52:53], v[52:53], 0, s[22:23]
	v_lshl_add_u64 v[52:53], v[52:53], 0, v[138:139]
	global_store_dwordx2 v[52:53], v[50:51], off
.LBB0_2607:
	s_or_b64 exec, exec, s[18:19]
	v_add_u32_e32 v50, 0x90, v140
	s_movk_i32 s0, 0x210
	v_cmp_gt_i32_e32 vcc, s0, v50
	s_and_saveexec_b64 s[18:19], vcc
	s_cbranch_execz .LBB0_2609
	v_readlane_b32 s22, v246, 9
	v_ashrrev_i32_e32 v51, 31, v50
	v_readlane_b32 s23, v246, 10
	v_lshl_add_u64 v[54:55], s[16:17], 0, v[50:51]
	v_lshlrev_b32_e32 v52, 5, v50
	v_readlane_b32 s0, v246, 49
	v_mov_b64_e32 v[50:51], s[22:23]
	s_movk_i32 s20, 0x600
	s_lshl_b32 s0, s0, 8
	v_mad_u64_u32 v[50:51], s[22:23], v54, s20, v[50:51]
	s_or_b32 s28, s0, s47
	v_mov_b32_e32 v54, v51
	v_or_b32_e32 v56, s28, v190
	v_mad_u64_u32 v[54:55], s[22:23], v55, s20, v[54:55]
	s_ashr_i32 s0, s28, 4
	v_mov_b32_e32 v51, v54
	v_ashrrev_i32_e32 v57, 31, v56
	s_lshl_b64 s[22:23], s[14:15], 2
	v_lshl_add_u64 v[54:55], v[56:57], 1, v[50:51]
	s_add_u32 s44, s48, s22
	s_nop 0
	s_addc_u32 s45, s49, s23
	s_nop 0
	v_readlane_b32 s56, v246, 17
	v_readlane_b32 s57, v246, 18
	s_lshl_b64 s[22:23], s[14:15], 1
	v_mov_b32_e32 v139, v191
	s_ashr_i32 s29, s28, 31
	s_nop 0
	v_lshlrev_b32_e32 v60, 16, v206
	v_and_b32_e32 v61, 0xffff0000, v206
	v_pk_fma_f32 v[46:47], v[160:161], v[60:61], v[46:47]
	s_nop 0
	v_mul_f32_e32 v53, 0x3d372713, v46
	v_mul_f32_e32 v53, v46, v53
	v_fma_f32 v53, v46, v53, v46
	v_mul_f32_e32 v53, 0x3f4c422a, v53
	v_add_f32_e32 v53, v53, v53
	v_mul_f32_e32 v53, 0x3fb8aa3b, v53
	v_exp_f32_e32 v53, v53
	s_nop 0
	v_add_f32_e32 v53, 1.0, v53
	v_rcp_f32_e32 v54, v53
	v_mul_f32_e32 v53, 0x3d372713, v47
	v_mul_f32_e32 v53, v47, v53
	v_fma_f32 v53, v47, v53, v47
	v_mul_f32_e32 v53, 0x3f4c422a, v53
	v_add_f32_e32 v53, v53, v53
	v_mul_f32_e32 v53, 0x3fb8aa3b, v53
	v_exp_f32_e32 v53, v53
	v_pk_mul_f32 v[46:47], v[46:47], 0.5 op_sel_hi:[1,0]
	v_add_f32_e32 v53, 1.0, v53
	v_rcp_f32_e32 v55, v53
	s_nop 0
	v_pk_fma_f32 v[54:55], v[54:55], 2.0, 1.0 op_sel_hi:[1,0,0] neg_lo:[1,0,0] neg_hi:[1,0,0]
	s_nop 0
	v_pk_add_f32 v[54:55], v[54:55], 1.0 op_sel_hi:[1,0]
	s_nop 0
	v_pk_mul_f32 v[46:47], v[46:47], v[54:55]
	v_lshlrev_b32_e32 v54, 16, v207
	v_and_b32_e32 v55, 0xffff0000, v207
	v_pk_fma_f32 v[48:49], v[162:163], v[54:55], v[48:49]
	v_cvt_pk_bf16_f32 v46, v46, v47
	v_mul_f32_e32 v47, 0x3d372713, v48
	v_mul_f32_e32 v47, v48, v47
	v_fma_f32 v47, v48, v47, v48
	v_mul_f32_e32 v47, 0x3f4c422a, v47
	v_add_f32_e32 v47, v47, v47
	v_mul_f32_e32 v47, 0x3fb8aa3b, v47
	v_exp_f32_e32 v47, v47
	s_nop 0
	v_add_f32_e32 v47, 1.0, v47
	v_rcp_f32_e32 v54, v47
	v_mul_f32_e32 v47, 0x3d372713, v49
	v_mul_f32_e32 v47, v49, v47
	v_fma_f32 v47, v49, v47, v49
	v_mul_f32_e32 v47, 0x3f4c422a, v47
	v_add_f32_e32 v47, v47, v47
	v_mul_f32_e32 v47, 0x3fb8aa3b, v47
	v_exp_f32_e32 v47, v47
	v_pk_mul_f32 v[48:49], v[48:49], 0.5 op_sel_hi:[1,0]
	v_add_f32_e32 v47, 1.0, v47
	v_rcp_f32_e32 v55, v47
	s_nop 0
	v_pk_fma_f32 v[54:55], v[54:55], 2.0, 1.0 op_sel_hi:[1,0,0] neg_lo:[1,0,0] neg_hi:[1,0,0]
	s_nop 0
	v_pk_add_f32 v[54:55], v[54:55], 1.0 op_sel_hi:[1,0]
	s_nop 0
	v_pk_mul_f32 v[48:49], v[48:49], v[54:55]
	s_nop 0
	v_cvt_pk_bf16_f32 v47, v48, v49
	v_add_u32_e32 v48, s0, v52
	v_ashrrev_i32_e32 v49, 31, v48
	v_lshlrev_b64 v[48:49], 10, v[48:49]
	v_lshl_add_u64 v[48:49], s[56:57], 0, v[48:49]
	v_lshl_add_u64 v[48:49], v[48:49], 0, s[22:23]
	v_lshl_add_u64 v[48:49], v[48:49], 0, v[138:139]
	global_store_dwordx2 v[48:49], v[46:47], off
	v_lshl_add_u64 v[46:47], s[28:29], 0, v[190:191]
	v_lshl_add_u64 v[46:47], v[46:47], 1, v[50:51]
	s_nop 0
	s_nop 0
	s_or_b32 s0, s28, 16
	s_ashr_i32 s0, s0, 4
	s_nop 0
	v_lshlrev_b32_e32 v56, 16, v208
	v_and_b32_e32 v57, 0xffff0000, v208
	s_nop 0
	v_pk_fma_f32 v[42:43], v[160:161], v[56:57], v[42:43]
	s_nop 0
	v_mul_f32_e32 v48, 0x3d372713, v42
	v_mul_f32_e32 v49, 0x3d372713, v43
	v_mul_f32_e32 v48, v42, v48
	v_mul_f32_e32 v49, v43, v49
	v_fma_f32 v48, v42, v48, v42
	v_fma_f32 v49, v43, v49, v43
	v_mul_f32_e32 v48, 0x3f4c422a, v48
	v_mul_f32_e32 v49, 0x3f4c422a, v49
	v_add_f32_e32 v48, v48, v48
	v_add_f32_e32 v49, v49, v49
	v_mul_f32_e32 v48, 0x3fb8aa3b, v48
	v_mul_f32_e32 v49, 0x3fb8aa3b, v49
	v_exp_f32_e32 v48, v48
	v_exp_f32_e32 v49, v49
	v_pk_mul_f32 v[42:43], v[42:43], 0.5 op_sel_hi:[1,0]
	v_add_f32_e32 v48, 1.0, v48
	v_add_f32_e32 v49, 1.0, v49
	v_rcp_f32_e32 v48, v48
	v_rcp_f32_e32 v49, v49
	s_nop 0
	v_pk_fma_f32 v[48:49], v[48:49], 2.0, 1.0 op_sel_hi:[1,0,0] neg_lo:[1,0,0] neg_hi:[1,0,0]
	s_nop 0
	v_pk_add_f32 v[48:49], v[48:49], 1.0 op_sel_hi:[1,0]
	s_nop 0
	v_pk_mul_f32 v[42:43], v[42:43], v[48:49]
	v_lshlrev_b32_e32 v48, 16, v209
	v_and_b32_e32 v49, 0xffff0000, v209
	v_pk_fma_f32 v[44:45], v[162:163], v[48:49], v[44:45]
	v_cvt_pk_bf16_f32 v42, v42, v43
	v_mul_f32_e32 v43, 0x3d372713, v44
	v_mul_f32_e32 v43, v44, v43
	v_fma_f32 v43, v44, v43, v44
	v_mul_f32_e32 v43, 0x3f4c422a, v43
	v_add_f32_e32 v43, v43, v43
	v_mul_f32_e32 v43, 0x3fb8aa3b, v43
	v_exp_f32_e32 v43, v43
	s_nop 0
	v_add_f32_e32 v43, 1.0, v43
	v_rcp_f32_e32 v48, v43
	v_mul_f32_e32 v43, 0x3d372713, v45
	v_mul_f32_e32 v43, v45, v43
	v_fma_f32 v43, v45, v43, v45
	v_mul_f32_e32 v43, 0x3f4c422a, v43
	v_add_f32_e32 v43, v43, v43
	v_mul_f32_e32 v43, 0x3fb8aa3b, v43
	v_exp_f32_e32 v43, v43
	v_pk_mul_f32 v[44:45], v[44:45], 0.5 op_sel_hi:[1,0]
	v_add_f32_e32 v43, 1.0, v43
	v_rcp_f32_e32 v49, v43
	s_nop 0
	v_pk_fma_f32 v[48:49], v[48:49], 2.0, 1.0 op_sel_hi:[1,0,0] neg_lo:[1,0,0] neg_hi:[1,0,0]
	s_nop 0
	v_pk_add_f32 v[48:49], v[48:49], 1.0 op_sel_hi:[1,0]
	s_nop 0
	v_pk_mul_f32 v[44:45], v[44:45], v[48:49]
	s_nop 0
	v_cvt_pk_bf16_f32 v43, v44, v45
	v_add_u32_e32 v44, s0, v52
	v_ashrrev_i32_e32 v45, 31, v44
	v_lshlrev_b64 v[44:45], 10, v[44:45]
	v_lshl_add_u64 v[44:45], s[56:57], 0, v[44:45]
	v_lshl_add_u64 v[44:45], v[44:45], 0, s[22:23]
	v_lshl_add_u64 v[44:45], v[44:45], 0, v[138:139]
	global_store_dwordx2 v[44:45], v[42:43], off
	s_nop 0
	s_nop 0
	s_nop 0
	s_or_b32 s0, s28, 0x80
	s_ashr_i32 s0, s0, 4
	s_nop 0
	v_lshlrev_b32_e32 v50, 16, v210
	v_and_b32_e32 v51, 0xffff0000, v210
	s_nop 0
	v_pk_fma_f32 v[38:39], v[160:161], v[50:51], v[38:39]
	s_nop 0
	v_mul_f32_e32 v42, 0x3d372713, v38
	v_mul_f32_e32 v43, 0x3d372713, v39
	v_mul_f32_e32 v42, v38, v42
	v_mul_f32_e32 v43, v39, v43
	v_fma_f32 v42, v38, v42, v38
	v_fma_f32 v43, v39, v43, v39
	v_mul_f32_e32 v42, 0x3f4c422a, v42
	v_mul_f32_e32 v43, 0x3f4c422a, v43
	v_add_f32_e32 v42, v42, v42
	v_add_f32_e32 v43, v43, v43
	v_mul_f32_e32 v42, 0x3fb8aa3b, v42
	v_mul_f32_e32 v43, 0x3fb8aa3b, v43
	v_exp_f32_e32 v42, v42
	v_exp_f32_e32 v43, v43
	v_pk_mul_f32 v[38:39], v[38:39], 0.5 op_sel_hi:[1,0]
	v_add_f32_e32 v42, 1.0, v42
	v_add_f32_e32 v43, 1.0, v43
	v_rcp_f32_e32 v42, v42
	v_rcp_f32_e32 v43, v43
	s_nop 0
	v_pk_fma_f32 v[42:43], v[42:43], 2.0, 1.0 op_sel_hi:[1,0,0] neg_lo:[1,0,0] neg_hi:[1,0,0]
	s_nop 0
	v_pk_add_f32 v[42:43], v[42:43], 1.0 op_sel_hi:[1,0]
	s_nop 0
	v_pk_mul_f32 v[38:39], v[38:39], v[42:43]
	v_lshlrev_b32_e32 v42, 16, v211
	v_and_b32_e32 v43, 0xffff0000, v211
	v_pk_fma_f32 v[40:41], v[162:163], v[42:43], v[40:41]
	v_cvt_pk_bf16_f32 v38, v38, v39
	v_mul_f32_e32 v39, 0x3d372713, v40
	v_mul_f32_e32 v39, v40, v39
	v_fma_f32 v39, v40, v39, v40
	v_mul_f32_e32 v39, 0x3f4c422a, v39
	v_add_f32_e32 v39, v39, v39
	v_mul_f32_e32 v39, 0x3fb8aa3b, v39
	v_exp_f32_e32 v39, v39
	s_nop 0
	v_add_f32_e32 v39, 1.0, v39
	v_rcp_f32_e32 v42, v39
	v_mul_f32_e32 v39, 0x3d372713, v41
	v_mul_f32_e32 v39, v41, v39
	v_fma_f32 v39, v41, v39, v41
	v_mul_f32_e32 v39, 0x3f4c422a, v39
	v_add_f32_e32 v39, v39, v39
	v_mul_f32_e32 v39, 0x3fb8aa3b, v39
	v_exp_f32_e32 v39, v39
	v_pk_mul_f32 v[40:41], v[40:41], 0.5 op_sel_hi:[1,0]
	v_add_f32_e32 v39, 1.0, v39
	v_rcp_f32_e32 v43, v39
	s_nop 0
	v_pk_fma_f32 v[42:43], v[42:43], 2.0, 1.0 op_sel_hi:[1,0,0] neg_lo:[1,0,0] neg_hi:[1,0,0]
	s_nop 0
	v_pk_add_f32 v[42:43], v[42:43], 1.0 op_sel_hi:[1,0]
	s_nop 0
	v_pk_mul_f32 v[40:41], v[40:41], v[42:43]
	s_nop 0
	v_cvt_pk_bf16_f32 v39, v40, v41
	v_add_u32_e32 v40, s0, v52
	v_ashrrev_i32_e32 v41, 31, v40
	v_lshlrev_b64 v[40:41], 10, v[40:41]
	v_lshl_add_u64 v[40:41], s[56:57], 0, v[40:41]
	v_lshl_add_u64 v[40:41], v[40:41], 0, s[22:23]
	v_lshl_add_u64 v[40:41], v[40:41], 0, v[138:139]
	global_store_dwordx2 v[40:41], v[38:39], off
	s_nop 0
	s_nop 0
	s_nop 0
	s_or_b32 s0, s28, 0x90
	s_ashr_i32 s0, s0, 4
	s_nop 0
	v_lshlrev_b32_e32 v44, 16, v212
	v_and_b32_e32 v45, 0xffff0000, v212
	s_nop 0
	v_pk_fma_f32 v[34:35], v[160:161], v[44:45], v[34:35]
	s_nop 0
	v_mul_f32_e32 v38, 0x3d372713, v34
	v_mul_f32_e32 v39, 0x3d372713, v35
	v_mul_f32_e32 v38, v34, v38
	v_mul_f32_e32 v39, v35, v39
	v_fma_f32 v38, v34, v38, v34
	v_fma_f32 v39, v35, v39, v35
	v_mul_f32_e32 v38, 0x3f4c422a, v38
	v_mul_f32_e32 v39, 0x3f4c422a, v39
	v_add_f32_e32 v38, v38, v38
	v_add_f32_e32 v39, v39, v39
	v_mul_f32_e32 v38, 0x3fb8aa3b, v38
	v_mul_f32_e32 v39, 0x3fb8aa3b, v39
	v_exp_f32_e32 v38, v38
	v_exp_f32_e32 v39, v39
	v_pk_mul_f32 v[34:35], v[34:35], 0.5 op_sel_hi:[1,0]
	v_add_f32_e32 v38, 1.0, v38
	v_add_f32_e32 v39, 1.0, v39
	v_rcp_f32_e32 v38, v38
	v_rcp_f32_e32 v39, v39
	s_nop 0
	v_pk_fma_f32 v[38:39], v[38:39], 2.0, 1.0 op_sel_hi:[1,0,0] neg_lo:[1,0,0] neg_hi:[1,0,0]
	s_nop 0
	v_pk_add_f32 v[38:39], v[38:39], 1.0 op_sel_hi:[1,0]
	s_nop 0
	v_pk_mul_f32 v[34:35], v[34:35], v[38:39]
	v_lshlrev_b32_e32 v38, 16, v213
	v_and_b32_e32 v39, 0xffff0000, v213
	v_pk_fma_f32 v[36:37], v[162:163], v[38:39], v[36:37]
	v_cvt_pk_bf16_f32 v34, v34, v35
	v_mul_f32_e32 v35, 0x3d372713, v36
	v_mul_f32_e32 v35, v36, v35
	v_fma_f32 v35, v36, v35, v36
	v_mul_f32_e32 v35, 0x3f4c422a, v35
	v_add_f32_e32 v35, v35, v35
	v_mul_f32_e32 v35, 0x3fb8aa3b, v35
	v_exp_f32_e32 v35, v35
	s_nop 0
	v_add_f32_e32 v35, 1.0, v35
	v_rcp_f32_e32 v38, v35
	v_mul_f32_e32 v35, 0x3d372713, v37
	v_mul_f32_e32 v35, v37, v35
	v_fma_f32 v35, v37, v35, v37
	v_mul_f32_e32 v35, 0x3f4c422a, v35
	v_add_f32_e32 v35, v35, v35
	v_mul_f32_e32 v35, 0x3fb8aa3b, v35
	v_exp_f32_e32 v35, v35
	v_pk_mul_f32 v[36:37], v[36:37], 0.5 op_sel_hi:[1,0]
	v_add_f32_e32 v35, 1.0, v35
	v_rcp_f32_e32 v39, v35
	s_nop 0
	v_pk_fma_f32 v[38:39], v[38:39], 2.0, 1.0 op_sel_hi:[1,0,0] neg_lo:[1,0,0] neg_hi:[1,0,0]
	s_nop 0
	v_pk_add_f32 v[38:39], v[38:39], 1.0 op_sel_hi:[1,0]
	s_nop 0
	v_pk_mul_f32 v[36:37], v[36:37], v[38:39]
	s_nop 0
	v_cvt_pk_bf16_f32 v35, v36, v37
	v_add_u32_e32 v36, s0, v52
	v_ashrrev_i32_e32 v37, 31, v36
	v_lshlrev_b64 v[36:37], 10, v[36:37]
	v_lshl_add_u64 v[36:37], s[56:57], 0, v[36:37]
	v_lshl_add_u64 v[36:37], v[36:37], 0, s[22:23]
	v_lshl_add_u64 v[36:37], v[36:37], 0, v[138:139]
	global_store_dwordx2 v[36:37], v[34:35], off
.LBB0_2609:
	s_or_b64 exec, exec, s[18:19]
	v_add_u32_e32 v34, 0xa0, v140
	s_movk_i32 s0, 0x210
	v_cmp_gt_i32_e32 vcc, s0, v34
	s_and_saveexec_b64 s[18:19], vcc
	s_cbranch_execz .LBB0_2611
	v_readlane_b32 s22, v246, 9
	v_ashrrev_i32_e32 v35, 31, v34
	v_readlane_b32 s23, v246, 10
	v_lshl_add_u64 v[38:39], s[16:17], 0, v[34:35]
	v_lshlrev_b32_e32 v36, 5, v34
	v_readlane_b32 s0, v246, 49
	v_mov_b64_e32 v[34:35], s[22:23]
	s_movk_i32 s20, 0x600
	s_lshl_b32 s0, s0, 8
	v_mad_u64_u32 v[34:35], s[22:23], v38, s20, v[34:35]
	s_or_b32 s28, s0, s47
	v_mov_b32_e32 v38, v35
	v_or_b32_e32 v40, s28, v190
	v_mad_u64_u32 v[38:39], s[22:23], v39, s20, v[38:39]
	s_ashr_i32 s0, s28, 4
	v_mov_b32_e32 v35, v38
	v_ashrrev_i32_e32 v41, 31, v40
	s_lshl_b64 s[22:23], s[14:15], 2
	v_lshl_add_u64 v[38:39], v[40:41], 1, v[34:35]
	s_add_u32 s44, s48, s22
	s_nop 0
	s_addc_u32 s45, s49, s23
	s_nop 0
	v_readlane_b32 s56, v246, 17
	v_readlane_b32 s57, v246, 18
	s_lshl_b64 s[22:23], s[14:15], 1
	v_mov_b32_e32 v139, v191
	s_ashr_i32 s29, s28, 31
	s_nop 0
	v_lshlrev_b32_e32 v44, 16, v214
	v_and_b32_e32 v45, 0xffff0000, v214
	v_pk_fma_f32 v[30:31], v[160:161], v[44:45], v[30:31]
	s_nop 0
	v_mul_f32_e32 v37, 0x3d372713, v30
	v_mul_f32_e32 v37, v30, v37
	v_fma_f32 v37, v30, v37, v30
	v_mul_f32_e32 v37, 0x3f4c422a, v37
	v_add_f32_e32 v37, v37, v37
	v_mul_f32_e32 v37, 0x3fb8aa3b, v37
	v_exp_f32_e32 v37, v37
	s_nop 0
	v_add_f32_e32 v37, 1.0, v37
	v_rcp_f32_e32 v38, v37
	v_mul_f32_e32 v37, 0x3d372713, v31
	v_mul_f32_e32 v37, v31, v37
	v_fma_f32 v37, v31, v37, v31
	v_mul_f32_e32 v37, 0x3f4c422a, v37
	v_add_f32_e32 v37, v37, v37
	v_mul_f32_e32 v37, 0x3fb8aa3b, v37
	v_exp_f32_e32 v37, v37
	v_pk_mul_f32 v[30:31], v[30:31], 0.5 op_sel_hi:[1,0]
	v_add_f32_e32 v37, 1.0, v37
	v_rcp_f32_e32 v39, v37
	s_nop 0
	v_pk_fma_f32 v[38:39], v[38:39], 2.0, 1.0 op_sel_hi:[1,0,0] neg_lo:[1,0,0] neg_hi:[1,0,0]
	s_nop 0
	v_pk_add_f32 v[38:39], v[38:39], 1.0 op_sel_hi:[1,0]
	s_nop 0
	v_pk_mul_f32 v[30:31], v[30:31], v[38:39]
	v_lshlrev_b32_e32 v38, 16, v215
	v_and_b32_e32 v39, 0xffff0000, v215
	v_pk_fma_f32 v[32:33], v[162:163], v[38:39], v[32:33]
	v_cvt_pk_bf16_f32 v30, v30, v31
	v_mul_f32_e32 v31, 0x3d372713, v32
	v_mul_f32_e32 v31, v32, v31
	v_fma_f32 v31, v32, v31, v32
	v_mul_f32_e32 v31, 0x3f4c422a, v31
	v_add_f32_e32 v31, v31, v31
	v_mul_f32_e32 v31, 0x3fb8aa3b, v31
	v_exp_f32_e32 v31, v31
	s_nop 0
	v_add_f32_e32 v31, 1.0, v31
	v_rcp_f32_e32 v38, v31
	v_mul_f32_e32 v31, 0x3d372713, v33
	v_mul_f32_e32 v31, v33, v31
	v_fma_f32 v31, v33, v31, v33
	v_mul_f32_e32 v31, 0x3f4c422a, v31
	v_add_f32_e32 v31, v31, v31
	v_mul_f32_e32 v31, 0x3fb8aa3b, v31
	v_exp_f32_e32 v31, v31
	v_pk_mul_f32 v[32:33], v[32:33], 0.5 op_sel_hi:[1,0]
	v_add_f32_e32 v31, 1.0, v31
	v_rcp_f32_e32 v39, v31
	s_nop 0
	v_pk_fma_f32 v[38:39], v[38:39], 2.0, 1.0 op_sel_hi:[1,0,0] neg_lo:[1,0,0] neg_hi:[1,0,0]
	s_nop 0
	v_pk_add_f32 v[38:39], v[38:39], 1.0 op_sel_hi:[1,0]
	s_nop 0
	v_pk_mul_f32 v[32:33], v[32:33], v[38:39]
	s_nop 0
	v_cvt_pk_bf16_f32 v31, v32, v33
	v_add_u32_e32 v32, s0, v36
	v_ashrrev_i32_e32 v33, 31, v32
	v_lshlrev_b64 v[32:33], 10, v[32:33]
	v_lshl_add_u64 v[32:33], s[56:57], 0, v[32:33]
	v_lshl_add_u64 v[32:33], v[32:33], 0, s[22:23]
	v_lshl_add_u64 v[32:33], v[32:33], 0, v[138:139]
	global_store_dwordx2 v[32:33], v[30:31], off
	v_lshl_add_u64 v[30:31], s[28:29], 0, v[190:191]
	v_lshl_add_u64 v[30:31], v[30:31], 1, v[34:35]
	s_nop 0
	s_nop 0
	s_or_b32 s0, s28, 16
	s_ashr_i32 s0, s0, 4
	s_nop 0
	v_lshlrev_b32_e32 v40, 16, v222
	v_and_b32_e32 v41, 0xffff0000, v222
	s_nop 0
	v_pk_fma_f32 v[26:27], v[160:161], v[40:41], v[26:27]
	s_nop 0
	v_mul_f32_e32 v32, 0x3d372713, v26
	v_mul_f32_e32 v33, 0x3d372713, v27
	v_mul_f32_e32 v32, v26, v32
	v_mul_f32_e32 v33, v27, v33
	v_fma_f32 v32, v26, v32, v26
	v_fma_f32 v33, v27, v33, v27
	v_mul_f32_e32 v32, 0x3f4c422a, v32
	v_mul_f32_e32 v33, 0x3f4c422a, v33
	v_add_f32_e32 v32, v32, v32
	v_add_f32_e32 v33, v33, v33
	v_mul_f32_e32 v32, 0x3fb8aa3b, v32
	v_mul_f32_e32 v33, 0x3fb8aa3b, v33
	v_exp_f32_e32 v32, v32
	v_exp_f32_e32 v33, v33
	v_pk_mul_f32 v[26:27], v[26:27], 0.5 op_sel_hi:[1,0]
	v_add_f32_e32 v32, 1.0, v32
	v_add_f32_e32 v33, 1.0, v33
	v_rcp_f32_e32 v32, v32
	v_rcp_f32_e32 v33, v33
	s_nop 0
	v_pk_fma_f32 v[32:33], v[32:33], 2.0, 1.0 op_sel_hi:[1,0,0] neg_lo:[1,0,0] neg_hi:[1,0,0]
	s_nop 0
	v_pk_add_f32 v[32:33], v[32:33], 1.0 op_sel_hi:[1,0]
	s_nop 0
	v_pk_mul_f32 v[26:27], v[26:27], v[32:33]
	v_lshlrev_b32_e32 v32, 16, v223
	v_and_b32_e32 v33, 0xffff0000, v223
	v_pk_fma_f32 v[28:29], v[162:163], v[32:33], v[28:29]
	v_cvt_pk_bf16_f32 v26, v26, v27
	v_mul_f32_e32 v27, 0x3d372713, v28
	v_mul_f32_e32 v27, v28, v27
	v_fma_f32 v27, v28, v27, v28
	v_mul_f32_e32 v27, 0x3f4c422a, v27
	v_add_f32_e32 v27, v27, v27
	v_mul_f32_e32 v27, 0x3fb8aa3b, v27
	v_exp_f32_e32 v27, v27
	s_nop 0
	v_add_f32_e32 v27, 1.0, v27
	v_rcp_f32_e32 v32, v27
	v_mul_f32_e32 v27, 0x3d372713, v29
	v_mul_f32_e32 v27, v29, v27
	v_fma_f32 v27, v29, v27, v29
	v_mul_f32_e32 v27, 0x3f4c422a, v27
	v_add_f32_e32 v27, v27, v27
	v_mul_f32_e32 v27, 0x3fb8aa3b, v27
	v_exp_f32_e32 v27, v27
	v_pk_mul_f32 v[28:29], v[28:29], 0.5 op_sel_hi:[1,0]
	v_add_f32_e32 v27, 1.0, v27
	v_rcp_f32_e32 v33, v27
	s_nop 0
	v_pk_fma_f32 v[32:33], v[32:33], 2.0, 1.0 op_sel_hi:[1,0,0] neg_lo:[1,0,0] neg_hi:[1,0,0]
	s_nop 0
	v_pk_add_f32 v[32:33], v[32:33], 1.0 op_sel_hi:[1,0]
	s_nop 0
	v_pk_mul_f32 v[28:29], v[28:29], v[32:33]
	s_nop 0
	v_cvt_pk_bf16_f32 v27, v28, v29
	v_add_u32_e32 v28, s0, v36
	v_ashrrev_i32_e32 v29, 31, v28
	v_lshlrev_b64 v[28:29], 10, v[28:29]
	v_lshl_add_u64 v[28:29], s[56:57], 0, v[28:29]
	v_lshl_add_u64 v[28:29], v[28:29], 0, s[22:23]
	v_lshl_add_u64 v[28:29], v[28:29], 0, v[138:139]
	global_store_dwordx2 v[28:29], v[26:27], off
	s_nop 0
	s_nop 0
	s_nop 0
	s_or_b32 s0, s28, 0x80
	s_ashr_i32 s0, s0, 4
	s_nop 0
	v_lshlrev_b32_e32 v34, 16, v224
	v_and_b32_e32 v35, 0xffff0000, v224
	s_nop 0
	v_pk_fma_f32 v[22:23], v[160:161], v[34:35], v[22:23]
	s_nop 0
	v_mul_f32_e32 v26, 0x3d372713, v22
	v_mul_f32_e32 v27, 0x3d372713, v23
	v_mul_f32_e32 v26, v22, v26
	v_mul_f32_e32 v27, v23, v27
	v_fma_f32 v26, v22, v26, v22
	v_fma_f32 v27, v23, v27, v23
	v_mul_f32_e32 v26, 0x3f4c422a, v26
	v_mul_f32_e32 v27, 0x3f4c422a, v27
	v_add_f32_e32 v26, v26, v26
	v_add_f32_e32 v27, v27, v27
	v_mul_f32_e32 v26, 0x3fb8aa3b, v26
	v_mul_f32_e32 v27, 0x3fb8aa3b, v27
	v_exp_f32_e32 v26, v26
	v_exp_f32_e32 v27, v27
	v_pk_mul_f32 v[22:23], v[22:23], 0.5 op_sel_hi:[1,0]
	v_add_f32_e32 v26, 1.0, v26
	v_add_f32_e32 v27, 1.0, v27
	v_rcp_f32_e32 v26, v26
	v_rcp_f32_e32 v27, v27
	s_nop 0
	v_pk_fma_f32 v[26:27], v[26:27], 2.0, 1.0 op_sel_hi:[1,0,0] neg_lo:[1,0,0] neg_hi:[1,0,0]
	s_nop 0
	v_pk_add_f32 v[26:27], v[26:27], 1.0 op_sel_hi:[1,0]
	s_nop 0
	v_pk_mul_f32 v[22:23], v[22:23], v[26:27]
	v_lshlrev_b32_e32 v26, 16, v225
	v_and_b32_e32 v27, 0xffff0000, v225
	v_pk_fma_f32 v[24:25], v[162:163], v[26:27], v[24:25]
	v_cvt_pk_bf16_f32 v22, v22, v23
	v_mul_f32_e32 v23, 0x3d372713, v24
	v_mul_f32_e32 v23, v24, v23
	v_fma_f32 v23, v24, v23, v24
	v_mul_f32_e32 v23, 0x3f4c422a, v23
	v_add_f32_e32 v23, v23, v23
	v_mul_f32_e32 v23, 0x3fb8aa3b, v23
	v_exp_f32_e32 v23, v23
	s_nop 0
	v_add_f32_e32 v23, 1.0, v23
	v_rcp_f32_e32 v26, v23
	v_mul_f32_e32 v23, 0x3d372713, v25
	v_mul_f32_e32 v23, v25, v23
	v_fma_f32 v23, v25, v23, v25
	v_mul_f32_e32 v23, 0x3f4c422a, v23
	v_add_f32_e32 v23, v23, v23
	v_mul_f32_e32 v23, 0x3fb8aa3b, v23
	v_exp_f32_e32 v23, v23
	v_pk_mul_f32 v[24:25], v[24:25], 0.5 op_sel_hi:[1,0]
	v_add_f32_e32 v23, 1.0, v23
	v_rcp_f32_e32 v27, v23
	s_nop 0
	v_pk_fma_f32 v[26:27], v[26:27], 2.0, 1.0 op_sel_hi:[1,0,0] neg_lo:[1,0,0] neg_hi:[1,0,0]
	s_nop 0
	v_pk_add_f32 v[26:27], v[26:27], 1.0 op_sel_hi:[1,0]
	s_nop 0
	v_pk_mul_f32 v[24:25], v[24:25], v[26:27]
	s_nop 0
	v_cvt_pk_bf16_f32 v23, v24, v25
	v_add_u32_e32 v24, s0, v36
	v_ashrrev_i32_e32 v25, 31, v24
	v_lshlrev_b64 v[24:25], 10, v[24:25]
	v_lshl_add_u64 v[24:25], s[56:57], 0, v[24:25]
	v_lshl_add_u64 v[24:25], v[24:25], 0, s[22:23]
	v_lshl_add_u64 v[24:25], v[24:25], 0, v[138:139]
	global_store_dwordx2 v[24:25], v[22:23], off
	s_nop 0
	s_nop 0
	s_nop 0
	s_or_b32 s0, s28, 0x90
	s_ashr_i32 s0, s0, 4
	s_nop 0
	v_lshlrev_b32_e32 v28, 16, v232
	v_and_b32_e32 v29, 0xffff0000, v232
	s_nop 0
	v_pk_fma_f32 v[18:19], v[160:161], v[28:29], v[18:19]
	s_nop 0
	v_mul_f32_e32 v22, 0x3d372713, v18
	v_mul_f32_e32 v23, 0x3d372713, v19
	v_mul_f32_e32 v22, v18, v22
	v_mul_f32_e32 v23, v19, v23
	v_fma_f32 v22, v18, v22, v18
	v_fma_f32 v23, v19, v23, v19
	v_mul_f32_e32 v22, 0x3f4c422a, v22
	v_mul_f32_e32 v23, 0x3f4c422a, v23
	v_add_f32_e32 v22, v22, v22
	v_add_f32_e32 v23, v23, v23
	v_mul_f32_e32 v22, 0x3fb8aa3b, v22
	v_mul_f32_e32 v23, 0x3fb8aa3b, v23
	v_exp_f32_e32 v22, v22
	v_exp_f32_e32 v23, v23
	v_pk_mul_f32 v[18:19], v[18:19], 0.5 op_sel_hi:[1,0]
	v_add_f32_e32 v22, 1.0, v22
	v_add_f32_e32 v23, 1.0, v23
	v_rcp_f32_e32 v22, v22
	v_rcp_f32_e32 v23, v23
	s_nop 0
	v_pk_fma_f32 v[22:23], v[22:23], 2.0, 1.0 op_sel_hi:[1,0,0] neg_lo:[1,0,0] neg_hi:[1,0,0]
	s_nop 0
	v_pk_add_f32 v[22:23], v[22:23], 1.0 op_sel_hi:[1,0]
	s_nop 0
	v_pk_mul_f32 v[18:19], v[18:19], v[22:23]
	v_lshlrev_b32_e32 v22, 16, v233
	v_and_b32_e32 v23, 0xffff0000, v233
	v_pk_fma_f32 v[20:21], v[162:163], v[22:23], v[20:21]
	v_cvt_pk_bf16_f32 v18, v18, v19
	v_mul_f32_e32 v19, 0x3d372713, v20
	v_mul_f32_e32 v19, v20, v19
	v_fma_f32 v19, v20, v19, v20
	v_mul_f32_e32 v19, 0x3f4c422a, v19
	v_add_f32_e32 v19, v19, v19
	v_mul_f32_e32 v19, 0x3fb8aa3b, v19
	v_exp_f32_e32 v19, v19
	s_nop 0
	v_add_f32_e32 v19, 1.0, v19
	v_rcp_f32_e32 v22, v19
	v_mul_f32_e32 v19, 0x3d372713, v21
	v_mul_f32_e32 v19, v21, v19
	v_fma_f32 v19, v21, v19, v21
	v_mul_f32_e32 v19, 0x3f4c422a, v19
	v_add_f32_e32 v19, v19, v19
	v_mul_f32_e32 v19, 0x3fb8aa3b, v19
	v_exp_f32_e32 v19, v19
	v_pk_mul_f32 v[20:21], v[20:21], 0.5 op_sel_hi:[1,0]
	v_add_f32_e32 v19, 1.0, v19
	v_rcp_f32_e32 v23, v19
	s_nop 0
	v_pk_fma_f32 v[22:23], v[22:23], 2.0, 1.0 op_sel_hi:[1,0,0] neg_lo:[1,0,0] neg_hi:[1,0,0]
	s_nop 0
	v_pk_add_f32 v[22:23], v[22:23], 1.0 op_sel_hi:[1,0]
	s_nop 0
	v_pk_mul_f32 v[20:21], v[20:21], v[22:23]
	s_nop 0
	v_cvt_pk_bf16_f32 v19, v20, v21
	v_add_u32_e32 v20, s0, v36
	v_ashrrev_i32_e32 v21, 31, v20
	v_lshlrev_b64 v[20:21], 10, v[20:21]
	v_lshl_add_u64 v[20:21], s[56:57], 0, v[20:21]
	v_lshl_add_u64 v[20:21], v[20:21], 0, s[22:23]
	v_lshl_add_u64 v[20:21], v[20:21], 0, v[138:139]
	global_store_dwordx2 v[20:21], v[18:19], off

.LBB0_2614:
	v_readlane_b32 s22, v246, 9
	v_ashrrev_i32_e32 v19, 31, v18
	v_readlane_b32 s23, v246, 10
	v_lshl_add_u64 v[22:23], s[16:17], 0, v[18:19]
	v_lshlrev_b32_e32 v20, 5, v18
	v_readlane_b32 s0, v246, 49
	v_mov_b64_e32 v[18:19], s[22:23]
	s_movk_i32 s17, 0x600
	s_lshl_b32 s0, s0, 8
	v_mad_u64_u32 v[18:19], s[22:23], v22, s17, v[18:19]
	s_or_b32 s16, s0, s47
	v_mov_b32_e32 v22, v19
	v_or_b32_e32 v24, s16, v190
	v_mad_u64_u32 v[22:23], s[22:23], v23, s17, v[22:23]
	s_ashr_i32 s0, s16, 4
	v_mov_b32_e32 v19, v22
	v_ashrrev_i32_e32 v25, 31, v24
	s_lshl_b64 s[22:23], s[14:15], 2
	v_lshl_add_u64 v[22:23], v[24:25], 1, v[18:19]
	s_add_u32 s22, s48, s22
	s_nop 0
	s_addc_u32 s23, s49, s23
	s_nop 0
	v_readlane_b32 s28, v246, 17
	v_readlane_b32 s29, v246, 18
	s_lshl_b64 s[14:15], s[14:15], 1
	v_mov_b32_e32 v139, v191
	s_ashr_i32 s17, s16, 31
	s_nop 0
	v_lshlrev_b32_e32 v28, 16, v234
	v_and_b32_e32 v29, 0xffff0000, v234
	v_pk_fma_f32 v[14:15], v[160:161], v[28:29], v[14:15]
	s_nop 0
	v_mul_f32_e32 v21, 0x3d372713, v14
	v_mul_f32_e32 v21, v14, v21
	v_fma_f32 v21, v14, v21, v14
	v_mul_f32_e32 v21, 0x3f4c422a, v21
	v_add_f32_e32 v21, v21, v21
	v_mul_f32_e32 v21, 0x3fb8aa3b, v21
	v_exp_f32_e32 v21, v21
	s_nop 0
	v_add_f32_e32 v21, 1.0, v21
	v_rcp_f32_e32 v22, v21
	v_mul_f32_e32 v21, 0x3d372713, v15
	v_mul_f32_e32 v21, v15, v21
	v_fma_f32 v21, v15, v21, v15
	v_mul_f32_e32 v21, 0x3f4c422a, v21
	v_add_f32_e32 v21, v21, v21
	v_mul_f32_e32 v21, 0x3fb8aa3b, v21
	v_exp_f32_e32 v21, v21
	v_pk_mul_f32 v[14:15], v[14:15], 0.5 op_sel_hi:[1,0]
	v_add_f32_e32 v21, 1.0, v21
	v_rcp_f32_e32 v23, v21
	s_nop 0
	v_pk_fma_f32 v[22:23], v[22:23], 2.0, 1.0 op_sel_hi:[1,0,0] neg_lo:[1,0,0] neg_hi:[1,0,0]
	s_nop 0
	v_pk_add_f32 v[22:23], v[22:23], 1.0 op_sel_hi:[1,0]
	s_nop 0
	v_pk_mul_f32 v[14:15], v[14:15], v[22:23]
	v_lshlrev_b32_e32 v22, 16, v235
	v_and_b32_e32 v23, 0xffff0000, v235
	v_pk_fma_f32 v[16:17], v[162:163], v[22:23], v[16:17]
	v_cvt_pk_bf16_f32 v14, v14, v15
	v_mul_f32_e32 v15, 0x3d372713, v16
	v_mul_f32_e32 v15, v16, v15
	v_fma_f32 v15, v16, v15, v16
	v_mul_f32_e32 v15, 0x3f4c422a, v15
	v_add_f32_e32 v15, v15, v15
	v_mul_f32_e32 v15, 0x3fb8aa3b, v15
	v_exp_f32_e32 v15, v15
	s_nop 0
	v_add_f32_e32 v15, 1.0, v15
	v_rcp_f32_e32 v22, v15
	v_mul_f32_e32 v15, 0x3d372713, v17
	v_mul_f32_e32 v15, v17, v15
	v_fma_f32 v15, v17, v15, v17
	v_mul_f32_e32 v15, 0x3f4c422a, v15
	v_add_f32_e32 v15, v15, v15
	v_mul_f32_e32 v15, 0x3fb8aa3b, v15
	v_exp_f32_e32 v15, v15
	v_pk_mul_f32 v[16:17], v[16:17], 0.5 op_sel_hi:[1,0]
	v_add_f32_e32 v15, 1.0, v15
	v_rcp_f32_e32 v23, v15
	s_nop 0
	v_pk_fma_f32 v[22:23], v[22:23], 2.0, 1.0 op_sel_hi:[1,0,0] neg_lo:[1,0,0] neg_hi:[1,0,0]
	s_nop 0
	v_pk_add_f32 v[22:23], v[22:23], 1.0 op_sel_hi:[1,0]
	s_nop 0
	v_pk_mul_f32 v[16:17], v[16:17], v[22:23]
	s_nop 0
	v_cvt_pk_bf16_f32 v15, v16, v17
	v_add_u32_e32 v16, s0, v20
	v_ashrrev_i32_e32 v17, 31, v16
	v_lshlrev_b64 v[16:17], 10, v[16:17]
	v_lshl_add_u64 v[16:17], s[28:29], 0, v[16:17]
	v_lshl_add_u64 v[16:17], v[16:17], 0, s[14:15]
	v_lshl_add_u64 v[16:17], v[16:17], 0, v[138:139]
	global_store_dwordx2 v[16:17], v[14:15], off
	v_lshl_add_u64 v[14:15], s[16:17], 0, v[190:191]
	v_lshl_add_u64 v[14:15], v[14:15], 1, v[18:19]
	s_nop 0
	s_nop 0
	s_or_b32 s0, s16, 16
	s_ashr_i32 s0, s0, 4
	s_nop 0
	v_lshlrev_b32_e32 v24, 16, v242
	v_and_b32_e32 v25, 0xffff0000, v242
	s_nop 0
	v_pk_fma_f32 v[10:11], v[160:161], v[24:25], v[10:11]
	s_nop 0
	v_mul_f32_e32 v16, 0x3d372713, v10
	v_mul_f32_e32 v17, 0x3d372713, v11
	v_mul_f32_e32 v16, v10, v16
	v_mul_f32_e32 v17, v11, v17
	v_fma_f32 v16, v10, v16, v10
	v_fma_f32 v17, v11, v17, v11
	v_mul_f32_e32 v16, 0x3f4c422a, v16
	v_mul_f32_e32 v17, 0x3f4c422a, v17
	v_add_f32_e32 v16, v16, v16
	v_add_f32_e32 v17, v17, v17
	v_mul_f32_e32 v16, 0x3fb8aa3b, v16
	v_mul_f32_e32 v17, 0x3fb8aa3b, v17
	v_exp_f32_e32 v16, v16
	v_exp_f32_e32 v17, v17
	v_pk_mul_f32 v[10:11], v[10:11], 0.5 op_sel_hi:[1,0]
	v_add_f32_e32 v16, 1.0, v16
	v_add_f32_e32 v17, 1.0, v17
	v_rcp_f32_e32 v16, v16
	v_rcp_f32_e32 v17, v17
	s_nop 0
	v_pk_fma_f32 v[16:17], v[16:17], 2.0, 1.0 op_sel_hi:[1,0,0] neg_lo:[1,0,0] neg_hi:[1,0,0]
	s_nop 0
	v_pk_add_f32 v[16:17], v[16:17], 1.0 op_sel_hi:[1,0]
	s_nop 0
	v_pk_mul_f32 v[10:11], v[10:11], v[16:17]
	v_lshlrev_b32_e32 v16, 16, v243
	v_and_b32_e32 v17, 0xffff0000, v243
	v_pk_fma_f32 v[12:13], v[162:163], v[16:17], v[12:13]
	v_cvt_pk_bf16_f32 v10, v10, v11
	v_mul_f32_e32 v11, 0x3d372713, v12
	v_mul_f32_e32 v11, v12, v11
	v_fma_f32 v11, v12, v11, v12
	v_mul_f32_e32 v11, 0x3f4c422a, v11
	v_add_f32_e32 v11, v11, v11
	v_mul_f32_e32 v11, 0x3fb8aa3b, v11
	v_exp_f32_e32 v11, v11
	s_nop 0
	v_add_f32_e32 v11, 1.0, v11
	v_rcp_f32_e32 v16, v11
	v_mul_f32_e32 v11, 0x3d372713, v13
	v_mul_f32_e32 v11, v13, v11
	v_fma_f32 v11, v13, v11, v13
	v_mul_f32_e32 v11, 0x3f4c422a, v11
	v_add_f32_e32 v11, v11, v11
	v_mul_f32_e32 v11, 0x3fb8aa3b, v11
	v_exp_f32_e32 v11, v11
	v_pk_mul_f32 v[12:13], v[12:13], 0.5 op_sel_hi:[1,0]
	v_add_f32_e32 v11, 1.0, v11
	v_rcp_f32_e32 v17, v11
	s_nop 0
	v_pk_fma_f32 v[16:17], v[16:17], 2.0, 1.0 op_sel_hi:[1,0,0] neg_lo:[1,0,0] neg_hi:[1,0,0]
	s_nop 0
	v_pk_add_f32 v[16:17], v[16:17], 1.0 op_sel_hi:[1,0]
	s_nop 0
	v_pk_mul_f32 v[12:13], v[12:13], v[16:17]
	s_nop 0
	v_cvt_pk_bf16_f32 v11, v12, v13
	v_add_u32_e32 v12, s0, v20
	v_ashrrev_i32_e32 v13, 31, v12
	v_lshlrev_b64 v[12:13], 10, v[12:13]
	v_lshl_add_u64 v[12:13], s[28:29], 0, v[12:13]
	v_lshl_add_u64 v[12:13], v[12:13], 0, s[14:15]
	v_lshl_add_u64 v[12:13], v[12:13], 0, v[138:139]
	global_store_dwordx2 v[12:13], v[10:11], off
	s_nop 0
	s_nop 0
	s_nop 0
	s_or_b32 s0, s16, 0x80
	s_ashr_i32 s0, s0, 4
	s_nop 0
	v_lshlrev_b32_e32 v18, 16, v244
	v_and_b32_e32 v19, 0xffff0000, v244
	s_nop 0
	v_pk_fma_f32 v[6:7], v[160:161], v[18:19], v[6:7]
	s_nop 0
	v_mul_f32_e32 v10, 0x3d372713, v6
	v_mul_f32_e32 v11, 0x3d372713, v7
	v_mul_f32_e32 v10, v6, v10
	v_mul_f32_e32 v11, v7, v11
	v_fma_f32 v10, v6, v10, v6
	v_fma_f32 v11, v7, v11, v7
	v_mul_f32_e32 v10, 0x3f4c422a, v10
	v_mul_f32_e32 v11, 0x3f4c422a, v11
	v_add_f32_e32 v10, v10, v10
	v_add_f32_e32 v11, v11, v11
	v_mul_f32_e32 v10, 0x3fb8aa3b, v10
	v_mul_f32_e32 v11, 0x3fb8aa3b, v11
	v_exp_f32_e32 v10, v10
	v_exp_f32_e32 v11, v11
	v_pk_mul_f32 v[6:7], v[6:7], 0.5 op_sel_hi:[1,0]
	v_add_f32_e32 v10, 1.0, v10
	v_add_f32_e32 v11, 1.0, v11
	v_rcp_f32_e32 v10, v10
	v_rcp_f32_e32 v11, v11
	s_nop 0
	v_pk_fma_f32 v[10:11], v[10:11], 2.0, 1.0 op_sel_hi:[1,0,0] neg_lo:[1,0,0] neg_hi:[1,0,0]
	s_nop 0
	v_pk_add_f32 v[10:11], v[10:11], 1.0 op_sel_hi:[1,0]
	s_nop 0
	v_pk_mul_f32 v[6:7], v[6:7], v[10:11]
	v_lshlrev_b32_e32 v10, 16, v245
	v_and_b32_e32 v11, 0xffff0000, v245
	v_pk_fma_f32 v[8:9], v[162:163], v[10:11], v[8:9]
	v_cvt_pk_bf16_f32 v6, v6, v7
	v_mul_f32_e32 v7, 0x3d372713, v8
	v_mul_f32_e32 v7, v8, v7
	v_fma_f32 v7, v8, v7, v8
	v_mul_f32_e32 v7, 0x3f4c422a, v7
	v_add_f32_e32 v7, v7, v7
	v_mul_f32_e32 v7, 0x3fb8aa3b, v7
	v_exp_f32_e32 v7, v7
	s_nop 0
	v_add_f32_e32 v7, 1.0, v7
	v_rcp_f32_e32 v10, v7
	v_mul_f32_e32 v7, 0x3d372713, v9
	v_mul_f32_e32 v7, v9, v7
	v_fma_f32 v7, v9, v7, v9
	v_mul_f32_e32 v7, 0x3f4c422a, v7
	v_add_f32_e32 v7, v7, v7
	v_mul_f32_e32 v7, 0x3fb8aa3b, v7
	v_exp_f32_e32 v7, v7
	v_pk_mul_f32 v[8:9], v[8:9], 0.5 op_sel_hi:[1,0]
	v_add_f32_e32 v7, 1.0, v7
	v_rcp_f32_e32 v11, v7
	s_nop 0
	v_pk_fma_f32 v[10:11], v[10:11], 2.0, 1.0 op_sel_hi:[1,0,0] neg_lo:[1,0,0] neg_hi:[1,0,0]
	s_nop 0
	v_pk_add_f32 v[10:11], v[10:11], 1.0 op_sel_hi:[1,0]
	s_nop 0
	v_pk_mul_f32 v[8:9], v[8:9], v[10:11]
	s_nop 0
	v_cvt_pk_bf16_f32 v7, v8, v9
	v_add_u32_e32 v8, s0, v20
	v_ashrrev_i32_e32 v9, 31, v8
	v_lshlrev_b64 v[8:9], 10, v[8:9]
	v_lshl_add_u64 v[8:9], s[28:29], 0, v[8:9]
	v_lshl_add_u64 v[8:9], v[8:9], 0, s[14:15]
	v_lshl_add_u64 v[8:9], v[8:9], 0, v[138:139]
	global_store_dwordx2 v[8:9], v[6:7], off
	s_nop 0
	s_nop 0
	s_nop 0
	s_or_b32 s0, s16, 0x90
	s_ashr_i32 s0, s0, 4
	s_nop 0
	v_lshlrev_b32_e32 v12, 16, v228
	v_and_b32_e32 v13, 0xffff0000, v228
	s_nop 0
	v_pk_fma_f32 v[2:3], v[160:161], v[12:13], v[2:3]
	s_nop 0
	v_mul_f32_e32 v6, 0x3d372713, v2
	v_mul_f32_e32 v7, 0x3d372713, v3
	v_mul_f32_e32 v6, v2, v6
	v_mul_f32_e32 v7, v3, v7
	v_fma_f32 v6, v2, v6, v2
	v_fma_f32 v7, v3, v7, v3
	v_mul_f32_e32 v6, 0x3f4c422a, v6
	v_mul_f32_e32 v7, 0x3f4c422a, v7
	v_add_f32_e32 v6, v6, v6
	v_add_f32_e32 v7, v7, v7
	v_mul_f32_e32 v6, 0x3fb8aa3b, v6
	v_mul_f32_e32 v7, 0x3fb8aa3b, v7
	v_exp_f32_e32 v6, v6
	v_exp_f32_e32 v7, v7
	v_pk_mul_f32 v[2:3], v[2:3], 0.5 op_sel_hi:[1,0]
	v_add_f32_e32 v6, 1.0, v6
	v_add_f32_e32 v7, 1.0, v7
	v_rcp_f32_e32 v6, v6
	v_rcp_f32_e32 v7, v7
	s_nop 0
	v_pk_fma_f32 v[6:7], v[6:7], 2.0, 1.0 op_sel_hi:[1,0,0] neg_lo:[1,0,0] neg_hi:[1,0,0]
	s_nop 0
	v_pk_add_f32 v[6:7], v[6:7], 1.0 op_sel_hi:[1,0]
	s_nop 0
	v_pk_mul_f32 v[2:3], v[2:3], v[6:7]
	v_lshlrev_b32_e32 v6, 16, v229
	v_and_b32_e32 v7, 0xffff0000, v229
	v_pk_fma_f32 v[4:5], v[162:163], v[6:7], v[4:5]
	v_cvt_pk_bf16_f32 v2, v2, v3
	v_mul_f32_e32 v3, 0x3d372713, v4
	v_mul_f32_e32 v3, v4, v3
	v_fma_f32 v3, v4, v3, v4
	v_mul_f32_e32 v3, 0x3f4c422a, v3
	v_add_f32_e32 v3, v3, v3
	v_mul_f32_e32 v3, 0x3fb8aa3b, v3
	v_exp_f32_e32 v3, v3
	s_nop 0
	v_add_f32_e32 v3, 1.0, v3
	v_rcp_f32_e32 v6, v3
	v_mul_f32_e32 v3, 0x3d372713, v5
	v_mul_f32_e32 v3, v5, v3
	v_fma_f32 v3, v5, v3, v5
	v_mul_f32_e32 v3, 0x3f4c422a, v3
	v_add_f32_e32 v3, v3, v3
	v_mul_f32_e32 v3, 0x3fb8aa3b, v3
	v_exp_f32_e32 v3, v3
	v_pk_mul_f32 v[4:5], v[4:5], 0.5 op_sel_hi:[1,0]
	v_add_f32_e32 v3, 1.0, v3
	v_rcp_f32_e32 v7, v3
	s_nop 0
	v_pk_fma_f32 v[6:7], v[6:7], 2.0, 1.0 op_sel_hi:[1,0,0] neg_lo:[1,0,0] neg_hi:[1,0,0]
	s_nop 0
	v_pk_add_f32 v[6:7], v[6:7], 1.0 op_sel_hi:[1,0]
	s_nop 0
	v_pk_mul_f32 v[4:5], v[4:5], v[6:7]
	s_nop 0
	v_cvt_pk_bf16_f32 v3, v4, v5
	v_add_u32_e32 v4, s0, v20
	v_ashrrev_i32_e32 v5, 31, v4
	v_lshlrev_b64 v[4:5], 10, v[4:5]
	v_lshl_add_u64 v[4:5], s[28:29], 0, v[4:5]
	v_lshl_add_u64 v[4:5], v[4:5], 0, s[14:15]
	v_lshl_add_u64 v[4:5], v[4:5], 0, v[138:139]
	global_store_dwordx2 v[4:5], v[2:3], off
	s_or_b64 exec, exec, s[18:19]
	s_and_b64 vcc, exec, s[42:43]
	s_mov_b64 s[14:15], -1
	s_cbranch_vccnz .LBB0_2613
